# 8x4 loops: half-tile staging (odd waves stage ks=1 sub-tiles at tile start, even waves stage ks=0 sub-tiles after a mid-tile barrier; 1.5 K-tile DMA window)
# baseline (speedup 1.0000x reference)
; #define LDB_(dst, ks) _Pragma("unroll") for (int n = 0; n < 4; ++n) dst[n] = *(const bf16x8*)(sB + b_off + n * 2048 + (ks) * 1024)
; #define LDA_(dst, ks, h) _Pragma("unroll") for (int m = 0; m < 4; ++m) dst[m] = *(const bf16x8*)(sA + a_off + ((h) * 4 + m) * 2048 + (ks) * 1024)
; #define MMA_(A, B, h) _Pragma("unroll") for (int m = 0; m < 4; ++m) _Pragma("unroll") for (int n = 0; n < 4; ++n) \
;       acc[(h) * 4 + m][n] = SWAP ? MFMA16(B[n], A[m], acc[(h) * 4 + m][n]) : MFMA16(A[m], B[n], acc[(h) * 4 + m][n])
; template <int MF, int NF, bool SWAP = true>
; DI void gemm_main(f32x4 (&acc)[MF][NF], const u16* __restrict__ Ab, int lda, const u16* __restrict__ Bb, int ldb,
;                   int K, char* shm) {
;     ...
;   for (int t = 0; t < nt; ++t) {
;     const int cur = RING3 ? cur3 : (t & 1);
;     if constexpr (RING3) {
;       if (t + 2 < nt) G_STAGE(nxt3, t + 2);
;     } else {
;       if (t + 1 < nt) G_STAGE(cur ^ 1, t + 1);
;     }
;     const char* sA = shm + cur * STAGE;
;     const char* sB = sA + TILE_A;
;     if constexpr (MF == 8 && NF == 4) {
;       bf16x8 B0[4], B1[4], A0[4], A1[4], A2[4], A3[4];
;     ...
;       LDB_(B0, 0); LDA_(A0, 0, 0);
;       LDA_(A1, 0, 1); MMA_(A0, B0, 0);
;       LDB_(B1, 1); LDA_(A2, 1, 0); MMA_(A1, B0, 1);
;       LDA_(A3, 1, 1); MMA_(A2, B1, 0);
;       MMA_(A3, B1, 1);
.LBB0_146:
	s_and_b32 s19, s17, 0x10000
	v_add_u32_e32 v137, s19, v132
	v_add_u32_e32 v178, v137, v131
	ds_read_b128 v[138:141], v178 offset:32768
	ds_read_b128 v[142:145], v178 offset:34816
	ds_read_b128 v[146:149], v178 offset:36864
	ds_read_b128 v[150:153], v178 offset:38912
	v_add_u32_e32 v137, v137, v129
	ds_read_b128 v[154:157], v137
	ds_read_b128 v[158:161], v137 offset:2048
	ds_read_b128 v[162:165], v137 offset:4096
	ds_read_b128 v[166:169], v137 offset:6144
	ds_read_b128 v[170:173], v137 offset:8192
	s_cmp_gt_u32 s13, 14
	s_cbranch_scc1 .Lg_rot146_last
	s_cmp_eq_u32 s13, 0
	s_cbranch_scc1 .Lg_rot146_first
	s_cmp_lg_u32 s26, 0
	s_cbranch_scc0 .Lg_rot146_ehead
	v_mfma_f32_16x16x32_bf16 v[60:63], v[186:189], v[190:193], v[60:63]
	s_xor_b32 s20, s19, 0x10000
	v_add_u32_e32 v179, s20, v128
	v_mfma_f32_16x16x32_bf16 v[56:59], v[194:197], v[190:193], v[56:59]
	s_nop 0
	v_readfirstlane_b32 s20, v179
	s_nop 1
	s_add_u32 m0, s20, 0x0
	v_mfma_f32_16x16x32_bf16 v[52:55], v[198:201], v[190:193], v[52:55]
	global_load_lds_dwordx4 v251, s[98:99]
	s_add_u32 m0, s20, 0x2000
	v_mfma_f32_16x16x32_bf16 v[48:51], v[212:215], v[190:193], v[48:51]
	global_load_lds_dwordx4 v250, s[98:99]
	s_add_u32 m0, s20, 0x4000
	v_mfma_f32_16x16x32_bf16 v[44:47], v[186:189], v[216:219], v[44:47]
	global_load_lds_dwordx4 v249, s[98:99]
	s_add_u32 m0, s20, 0x6000
	v_mfma_f32_16x16x32_bf16 v[40:43], v[194:197], v[216:219], v[40:43]
	global_load_lds_dwordx4 v248, s[98:99]
	s_add_u32 m0, s20, 0x8000
	v_mfma_f32_16x16x32_bf16 v[36:39], v[198:201], v[216:219], v[36:39]
	global_load_lds_dwordx4 v247, s[100:101]
	s_add_u32 m0, s20, 0xa000
	v_mfma_f32_16x16x32_bf16 v[32:35], v[212:215], v[216:219], v[32:35]
	global_load_lds_dwordx4 v246, s[100:101]
	s_add_u32 m0, s20, 0xc000
	v_mfma_f32_16x16x32_bf16 v[28:31], v[186:189], v[220:223], v[28:31]
	global_load_lds_dwordx4 v245, s[100:101]
	s_add_u32 m0, s20, 0xe000
	v_mfma_f32_16x16x32_bf16 v[24:27], v[194:197], v[220:223], v[24:27]
	global_load_lds_dwordx4 v244, s[100:101]
	v_mfma_f32_16x16x32_bf16 v[20:23], v[198:201], v[220:223], v[20:23]
	s_add_u32 s98, s98, 0x80
	s_addc_u32 s99, s99, 0
	s_add_u32 s100, s100, 0x80
	s_addc_u32 s101, s101, 0
	v_mfma_f32_16x16x32_bf16 v[16:19], v[212:215], v[220:223], v[16:19]
	v_mfma_f32_16x16x32_bf16 v[12:15], v[186:189], v[224:227], v[12:15]
	v_mfma_f32_16x16x32_bf16 v[8:11], v[194:197], v[224:227], v[8:11]
	v_mfma_f32_16x16x32_bf16 v[4:7], v[198:201], v[224:227], v[4:7]
	v_mfma_f32_16x16x32_bf16 v[0:3], v[212:215], v[224:227], v[0:3]
	s_branch .Lg_rot146_main
.Lg_rot146_ehead:
	v_mfma_f32_16x16x32_bf16 v[60:63], v[186:189], v[190:193], v[60:63]
	s_add_u32 s98, s98, 0x80
	s_addc_u32 s99, s99, 0
	s_add_u32 s100, s100, 0x80
	s_addc_u32 s101, s101, 0
	v_mfma_f32_16x16x32_bf16 v[56:59], v[194:197], v[190:193], v[56:59]
	v_mfma_f32_16x16x32_bf16 v[52:55], v[198:201], v[190:193], v[52:55]
	v_mfma_f32_16x16x32_bf16 v[48:51], v[212:215], v[190:193], v[48:51]
	v_mfma_f32_16x16x32_bf16 v[44:47], v[186:189], v[216:219], v[44:47]
	v_mfma_f32_16x16x32_bf16 v[40:43], v[194:197], v[216:219], v[40:43]
	v_mfma_f32_16x16x32_bf16 v[36:39], v[198:201], v[216:219], v[36:39]
	v_mfma_f32_16x16x32_bf16 v[32:35], v[212:215], v[216:219], v[32:35]
	v_mfma_f32_16x16x32_bf16 v[28:31], v[186:189], v[220:223], v[28:31]
	v_mfma_f32_16x16x32_bf16 v[24:27], v[194:197], v[220:223], v[24:27]
	v_mfma_f32_16x16x32_bf16 v[20:23], v[198:201], v[220:223], v[20:23]
	v_mfma_f32_16x16x32_bf16 v[16:19], v[212:215], v[220:223], v[16:19]
	v_mfma_f32_16x16x32_bf16 v[12:15], v[186:189], v[224:227], v[12:15]
	v_mfma_f32_16x16x32_bf16 v[8:11], v[194:197], v[224:227], v[8:11]
	v_mfma_f32_16x16x32_bf16 v[4:7], v[198:201], v[224:227], v[4:7]
	v_mfma_f32_16x16x32_bf16 v[0:3], v[212:215], v[224:227], v[0:3]
	s_branch .Lg_rot146_main
.Lg_rot146_first:
	v_add_u32_e32 v174, s11, v136
	s_xor_b32 s20, s19, 0x10000
	v_add_u32_e32 v176, 64, v174
	v_add_u32_e32 v179, s20, v128
	v_ashrrev_i32_e32 v177, 31, v176
	v_lshlrev_b64 v[176:177], 1, v[176:177]
	v_readfirstlane_b32 s20, v179
	v_lshl_add_u64 v[180:181], s[0:1], 0, v[176:177]
	s_mov_b32 m0, s20
	v_add_u32_e32 v182, 0x2000, v179
	global_load_lds_dwordx4 v[180:181], off
	v_subrev_u32_e32 v251, s0, v180
	v_add_u32_e32 v180, 0x10040, v174
	v_ashrrev_i32_e32 v181, 31, v180
	v_lshlrev_b64 v[180:181], 1, v[180:181]
	v_readfirstlane_b32 s20, v182
	v_lshl_add_u64 v[184:185], s[0:1], 0, v[180:181]
	s_mov_b32 m0, s20
	v_add_u32_e32 v175, 0x4000, v179
	global_load_lds_dwordx4 v[184:185], off
	v_subrev_u32_e32 v250, s0, v184
	v_add_u32_e32 v184, 0x20040, v174
	v_ashrrev_i32_e32 v185, 31, v184
	v_lshlrev_b64 v[184:185], 1, v[184:185]
	v_readfirstlane_b32 s20, v175
	v_lshl_add_u64 v[182:183], s[0:1], 0, v[184:185]
	s_mov_b32 m0, s20
	v_add_u32_e32 v211, 0x6000, v179
	global_load_lds_dwordx4 v[182:183], off
	v_subrev_u32_e32 v249, s0, v182
	v_add_u32_e32 v182, 0x30040, v174
	v_ashrrev_i32_e32 v183, 31, v182
	v_lshlrev_b64 v[182:183], 1, v[182:183]
	v_readfirstlane_b32 s20, v211
	v_lshl_add_u64 v[174:175], s[0:1], 0, v[182:183]
	s_mov_b32 m0, s20
	v_lshl_add_u64 v[176:177], s[4:5], 0, v[176:177]
	global_load_lds_dwordx4 v[174:175], off
	v_subrev_u32_e32 v248, s0, v174
	v_add_u32_e32 v174, 0x8000, v179
	s_nop 0
	v_readfirstlane_b32 s20, v174
	s_mov_b32 m0, s20
	s_nop 0
	global_load_lds_dwordx4 v[176:177], off
	v_subrev_u32_e32 v247, s4, v176
	v_lshl_add_u64 v[176:177], s[4:5], 0, v[180:181]
	v_add_u32_e32 v180, 0xa000, v179
	s_nop 0
	v_readfirstlane_b32 s20, v180
	v_add_u32_e32 v180, 0xc000, v179
	s_mov_b32 m0, s20
	v_readfirstlane_b32 s20, v180
	v_add_u32_e32 v179, 0xe000, v179
	global_load_lds_dwordx4 v[176:177], off
	v_subrev_u32_e32 v246, s4, v176
	v_lshl_add_u64 v[176:177], s[4:5], 0, v[184:185]
	s_mov_b32 m0, s20
	v_readfirstlane_b32 s20, v179
	global_load_lds_dwordx4 v[176:177], off
	v_subrev_u32_e32 v245, s4, v176
	v_lshl_add_u64 v[176:177], s[4:5], 0, v[182:183]
	s_mov_b32 m0, s20
	s_nop 0
	global_load_lds_dwordx4 v[176:177], off
	v_subrev_u32_e32 v244, s4, v176
	s_add_u32 s98, s0, 0x80
	s_addc_u32 s99, s1, 0
	s_add_u32 s100, s4, 0x80
	s_addc_u32 s101, s5, 0
	v_readfirstlane_b32 s26, v179
	s_bfe_u32 s26, s26, 0x1000a
	s_branch .Lg_rot146_main

; #define LDB_(dst, ks) _Pragma("unroll") for (int n = 0; n < 4; ++n) dst[n] = *(const bf16x8*)(sB + b_off + n * 2048 + (ks) * 1024)
; #define LDA_(dst, ks, h) _Pragma("unroll") for (int m = 0; m < 4; ++m) dst[m] = *(const bf16x8*)(sA + a_off + ((h) * 4 + m) * 2048 + (ks) * 1024)
; #define MMA_(A, B, h) _Pragma("unroll") for (int m = 0; m < 4; ++m) _Pragma("unroll") for (int n = 0; n < 4; ++n) \
;       acc[(h) * 4 + m][n] = SWAP ? MFMA16(B[n], A[m], acc[(h) * 4 + m][n]) : MFMA16(A[m], B[n], acc[(h) * 4 + m][n])
; template <int MF, int NF, bool SWAP = true>
; DI void gemm_main(f32x4 (&acc)[MF][NF], const u16* __restrict__ Ab, int lda, const u16* __restrict__ Bb, int ldb,
;                   int K, char* shm) {
;     ...
;     if constexpr (MF == 8 && NF == 4) {
;       bf16x8 B0[4], B1[4], A0[4], A1[4], A2[4], A3[4];
;     ...
;       LDB_(B0, 0); LDA_(A0, 0, 0);
;       LDA_(A1, 0, 1); MMA_(A0, B0, 0);
;       LDB_(B1, 1); LDA_(A2, 1, 0); MMA_(A1, B0, 1);
;       LDA_(A3, 1, 1); MMA_(A2, B1, 0);
;       MMA_(A3, B1, 1);
.Lg_rot146_main:
	s_waitcnt lgkmcnt(4)
	v_mfma_f32_16x16x32_bf16 v[124:127], v[138:141], v[154:157], v[124:127]
	v_mfma_f32_16x16x32_bf16 v[120:123], v[142:145], v[154:157], v[120:123]
	v_mfma_f32_16x16x32_bf16 v[116:119], v[146:149], v[154:157], v[116:119]
	v_mfma_f32_16x16x32_bf16 v[112:115], v[150:153], v[154:157], v[112:115]
	ds_read_b128 v[154:157], v137 offset:10240
	s_waitcnt lgkmcnt(4)
	v_mfma_f32_16x16x32_bf16 v[108:111], v[138:141], v[158:161], v[108:111]
	v_mfma_f32_16x16x32_bf16 v[104:107], v[142:145], v[158:161], v[104:107]
	v_mfma_f32_16x16x32_bf16 v[100:103], v[146:149], v[158:161], v[100:103]
	v_mfma_f32_16x16x32_bf16 v[96:99], v[150:153], v[158:161], v[96:99]
	ds_read_b128 v[158:161], v137 offset:12288
	s_waitcnt lgkmcnt(4)
	v_mfma_f32_16x16x32_bf16 v[92:95], v[138:141], v[162:165], v[92:95]
	v_mfma_f32_16x16x32_bf16 v[88:91], v[142:145], v[162:165], v[88:91]
	v_mfma_f32_16x16x32_bf16 v[84:87], v[146:149], v[162:165], v[84:87]
	v_mfma_f32_16x16x32_bf16 v[80:83], v[150:153], v[162:165], v[80:83]
	ds_read_b128 v[162:165], v137 offset:14336
	s_waitcnt lgkmcnt(4)
	v_mfma_f32_16x16x32_bf16 v[76:79], v[138:141], v[166:169], v[76:79]
	v_mfma_f32_16x16x32_bf16 v[72:75], v[142:145], v[166:169], v[72:75]
	v_mfma_f32_16x16x32_bf16 v[68:71], v[146:149], v[166:169], v[68:71]
	v_mfma_f32_16x16x32_bf16 v[64:67], v[150:153], v[166:169], v[64:67]
	s_waitcnt lgkmcnt(0)
	s_cmp_eq_u32 s26, 0
	s_cbranch_scc1 .Lg_rot146_mbar
	s_cmp_gt_u32 s13, 14
	s_cbranch_scc1 .Lg_rot146_mw0
	s_waitcnt vmcnt(8)
	s_branch .Lg_rot146_mbar

; #define LDB_(dst, ks) _Pragma("unroll") for (int n = 0; n < 4; ++n) dst[n] = *(const bf16x8*)(sB + b_off + n * 2048 + (ks) * 1024)
; #define LDA_(dst, ks, h) _Pragma("unroll") for (int m = 0; m < 4; ++m) dst[m] = *(const bf16x8*)(sA + a_off + ((h) * 4 + m) * 2048 + (ks) * 1024)
; #define MMA_(A, B, h) _Pragma("unroll") for (int m = 0; m < 4; ++m) _Pragma("unroll") for (int n = 0; n < 4; ++n) \
;       acc[(h) * 4 + m][n] = SWAP ? MFMA16(B[n], A[m], acc[(h) * 4 + m][n]) : MFMA16(A[m], B[n], acc[(h) * 4 + m][n])
; template <int MF, int NF, bool SWAP = true>
; DI void gemm_main(f32x4 (&acc)[MF][NF], const u16* __restrict__ Ab, int lda, const u16* __restrict__ Bb, int ldb,
;                   int K, char* shm) {
;     ...
;   for (int t = 0; t < nt; ++t) {
;     const int cur = RING3 ? cur3 : (t & 1);
;     if constexpr (RING3) {
;       if (t + 2 < nt) G_STAGE(nxt3, t + 2);
;     } else {
;       if (t + 1 < nt) G_STAGE(cur ^ 1, t + 1);
;     }
;     const char* sA = shm + cur * STAGE;
;     const char* sB = sA + TILE_A;
;     if constexpr (MF == 8 && NF == 4) {
;       bf16x8 B0[4], B1[4], A0[4], A1[4], A2[4], A3[4];
;     ...
;       LDB_(B0, 0); LDA_(A0, 0, 0);
;       LDA_(A1, 0, 1); MMA_(A0, B0, 0);
;       LDB_(B1, 1); LDA_(A2, 1, 0); MMA_(A1, B0, 1);
;       LDA_(A3, 1, 1); MMA_(A2, B1, 0);
;       MMA_(A3, B1, 1);
.Lg_rot146_mbar:
	s_barrier
	s_cmp_lg_u32 s26, 0
	s_cbranch_scc1 .Lg_rot146_bplain
	s_cmp_gt_u32 s13, 13
	s_cbranch_scc1 .Lg_rot146_bplain
	ds_read_b128 v[186:189], v178 offset:33792
	v_mfma_f32_16x16x32_bf16 v[60:63], v[138:141], v[170:173], v[60:63]
	v_add_u32_e32 v255, s19, v128
	s_nop 0
	v_readfirstlane_b32 s20, v255
	s_nop 1
	s_add_u32 m0, s20, 0x0
	v_mfma_f32_16x16x32_bf16 v[56:59], v[142:145], v[170:173], v[56:59]
	global_load_lds_dwordx4 v251, s[98:99]
	s_add_u32 m0, s20, 0x2000
	ds_read_b128 v[194:197], v178 offset:35840
	v_mfma_f32_16x16x32_bf16 v[52:55], v[146:149], v[170:173], v[52:55]
	global_load_lds_dwordx4 v250, s[98:99]
	s_add_u32 m0, s20, 0x4000
	v_mfma_f32_16x16x32_bf16 v[48:51], v[150:153], v[170:173], v[48:51]
	global_load_lds_dwordx4 v249, s[98:99]
	s_add_u32 m0, s20, 0x6000
	ds_read_b128 v[198:201], v178 offset:37888
	v_mfma_f32_16x16x32_bf16 v[44:47], v[138:141], v[154:157], v[44:47]
	global_load_lds_dwordx4 v248, s[98:99]
	s_add_u32 m0, s20, 0x8000
	v_mfma_f32_16x16x32_bf16 v[40:43], v[142:145], v[154:157], v[40:43]
	global_load_lds_dwordx4 v247, s[100:101]
	s_add_u32 m0, s20, 0xa000
	ds_read_b128 v[212:215], v178 offset:39936
	v_mfma_f32_16x16x32_bf16 v[36:39], v[146:149], v[154:157], v[36:39]
	global_load_lds_dwordx4 v246, s[100:101]
	s_add_u32 m0, s20, 0xc000
	v_mfma_f32_16x16x32_bf16 v[32:35], v[150:153], v[154:157], v[32:35]
	global_load_lds_dwordx4 v245, s[100:101]
	s_add_u32 m0, s20, 0xe000
	ds_read_b128 v[154:157], v137 offset:1024
	v_mfma_f32_16x16x32_bf16 v[28:31], v[138:141], v[158:161], v[28:31]
	global_load_lds_dwordx4 v244, s[100:101]
	v_mfma_f32_16x16x32_bf16 v[24:27], v[142:145], v[158:161], v[24:27]
	ds_read_b128 v[182:185], v137 offset:3072
	v_mfma_f32_16x16x32_bf16 v[20:23], v[146:149], v[158:161], v[20:23]
	v_mfma_f32_16x16x32_bf16 v[16:19], v[150:153], v[158:161], v[16:19]
	ds_read_b128 v[158:161], v137 offset:5120
	v_mfma_f32_16x16x32_bf16 v[12:15], v[138:141], v[162:165], v[12:15]
	v_mfma_f32_16x16x32_bf16 v[8:11], v[142:145], v[162:165], v[8:11]
	ds_read_b128 v[138:141], v137 offset:7168
	v_mfma_f32_16x16x32_bf16 v[4:7], v[146:149], v[162:165], v[4:7]
	v_mfma_f32_16x16x32_bf16 v[0:3], v[150:153], v[162:165], v[0:3]
	ds_read_b128 v[190:193], v137 offset:9216
	s_waitcnt lgkmcnt(4)
	v_mfma_f32_16x16x32_bf16 v[124:127], v[186:189], v[154:157], v[124:127]
	v_mfma_f32_16x16x32_bf16 v[120:123], v[194:197], v[154:157], v[120:123]
	v_mfma_f32_16x16x32_bf16 v[116:119], v[198:201], v[154:157], v[116:119]
	v_mfma_f32_16x16x32_bf16 v[112:115], v[212:215], v[154:157], v[112:115]
	ds_read_b128 v[216:219], v137 offset:11264
	s_waitcnt lgkmcnt(4)
	v_mfma_f32_16x16x32_bf16 v[108:111], v[186:189], v[182:185], v[108:111]
	v_mfma_f32_16x16x32_bf16 v[104:107], v[194:197], v[182:185], v[104:107]
	v_mfma_f32_16x16x32_bf16 v[100:103], v[198:201], v[182:185], v[100:103]
	v_mfma_f32_16x16x32_bf16 v[96:99], v[212:215], v[182:185], v[96:99]
	ds_read_b128 v[220:223], v137 offset:13312
	s_waitcnt lgkmcnt(4)
	v_mfma_f32_16x16x32_bf16 v[92:95], v[186:189], v[158:161], v[92:95]
	v_mfma_f32_16x16x32_bf16 v[88:91], v[194:197], v[158:161], v[88:91]
	v_mfma_f32_16x16x32_bf16 v[84:87], v[198:201], v[158:161], v[84:87]
	v_mfma_f32_16x16x32_bf16 v[80:83], v[212:215], v[158:161], v[80:83]
	ds_read_b128 v[224:227], v137 offset:15360
	s_waitcnt lgkmcnt(4)
	v_mfma_f32_16x16x32_bf16 v[76:79], v[186:189], v[138:141], v[76:79]
	v_mfma_f32_16x16x32_bf16 v[72:75], v[194:197], v[138:141], v[72:75]
	v_mfma_f32_16x16x32_bf16 v[68:71], v[198:201], v[138:141], v[68:71]
	v_mfma_f32_16x16x32_bf16 v[64:67], v[212:215], v[138:141], v[64:67]
	s_waitcnt lgkmcnt(0)
	s_waitcnt vmcnt(8)
	s_branch .Lg_rot146_ectl
; #define LDB_(dst, ks) _Pragma("unroll") for (int n = 0; n < 4; ++n) dst[n] = *(const bf16x8*)(sB + b_off + n * 2048 + (ks) * 1024)
; #define LDA_(dst, ks, h) _Pragma("unroll") for (int m = 0; m < 4; ++m) dst[m] = *(const bf16x8*)(sA + a_off + ((h) * 4 + m) * 2048 + (ks) * 1024)
; #define MMA_(A, B, h) _Pragma("unroll") for (int m = 0; m < 4; ++m) _Pragma("unroll") for (int n = 0; n < 4; ++n) \
;       acc[(h) * 4 + m][n] = SWAP ? MFMA16(B[n], A[m], acc[(h) * 4 + m][n]) : MFMA16(A[m], B[n], acc[(h) * 4 + m][n])
; template <int MF, int NF, bool SWAP = true>
; DI void gemm_main(f32x4 (&acc)[MF][NF], const u16* __restrict__ Ab, int lda, const u16* __restrict__ Bb, int ldb,
;                   int K, char* shm) {
;     ...
;     if constexpr (MF == 8 && NF == 4) {
;       bf16x8 B0[4], B1[4], A0[4], A1[4], A2[4], A3[4];
;     ...
;       LDB_(B0, 0); LDA_(A0, 0, 0);
;       LDA_(A1, 0, 1); MMA_(A0, B0, 0);
;       LDB_(B1, 1); LDA_(A2, 1, 0); MMA_(A1, B0, 1);
;       LDA_(A3, 1, 1); MMA_(A2, B1, 0);
;       MMA_(A3, B1, 1);
;     ...
;     if constexpr (RING3) {
;       if (t + 2 < nt) asm volatile("s_waitcnt vmcnt(6)" ::: "memory");
;       else asm volatile("s_waitcnt vmcnt(0)" ::: "memory");
;       asm volatile("s_waitcnt lgkmcnt(0)" ::: "memory");
;       __builtin_amdgcn_s_barrier();
;       cur3 = (cur3 == 2) ? 0 : cur3 + 1;
;       nxt3 = (nxt3 == 2) ? 0 : nxt3 + 1;
;     } else {
;       asm volatile("s_waitcnt vmcnt(0)" ::: "memory");
;       __syncthreads();
;     }
;   }
.Lg_rot146_bplain:
	ds_read_b128 v[186:189], v178 offset:33792
	v_mfma_f32_16x16x32_bf16 v[60:63], v[138:141], v[170:173], v[60:63]
	v_mfma_f32_16x16x32_bf16 v[56:59], v[142:145], v[170:173], v[56:59]
	ds_read_b128 v[194:197], v178 offset:35840
	v_mfma_f32_16x16x32_bf16 v[52:55], v[146:149], v[170:173], v[52:55]
	v_mfma_f32_16x16x32_bf16 v[48:51], v[150:153], v[170:173], v[48:51]
	ds_read_b128 v[198:201], v178 offset:37888
	v_mfma_f32_16x16x32_bf16 v[44:47], v[138:141], v[154:157], v[44:47]
	v_mfma_f32_16x16x32_bf16 v[40:43], v[142:145], v[154:157], v[40:43]
	ds_read_b128 v[212:215], v178 offset:39936
	v_mfma_f32_16x16x32_bf16 v[36:39], v[146:149], v[154:157], v[36:39]
	v_mfma_f32_16x16x32_bf16 v[32:35], v[150:153], v[154:157], v[32:35]
	ds_read_b128 v[154:157], v137 offset:1024
	v_mfma_f32_16x16x32_bf16 v[28:31], v[138:141], v[158:161], v[28:31]
	v_mfma_f32_16x16x32_bf16 v[24:27], v[142:145], v[158:161], v[24:27]
	ds_read_b128 v[182:185], v137 offset:3072
	v_mfma_f32_16x16x32_bf16 v[20:23], v[146:149], v[158:161], v[20:23]
	v_mfma_f32_16x16x32_bf16 v[16:19], v[150:153], v[158:161], v[16:19]
	ds_read_b128 v[158:161], v137 offset:5120
	v_mfma_f32_16x16x32_bf16 v[12:15], v[138:141], v[162:165], v[12:15]
	v_mfma_f32_16x16x32_bf16 v[8:11], v[142:145], v[162:165], v[8:11]
	ds_read_b128 v[138:141], v137 offset:7168
	v_mfma_f32_16x16x32_bf16 v[4:7], v[146:149], v[162:165], v[4:7]
	v_mfma_f32_16x16x32_bf16 v[0:3], v[150:153], v[162:165], v[0:3]
	ds_read_b128 v[190:193], v137 offset:9216
	s_waitcnt lgkmcnt(4)
	v_mfma_f32_16x16x32_bf16 v[124:127], v[186:189], v[154:157], v[124:127]
	v_mfma_f32_16x16x32_bf16 v[120:123], v[194:197], v[154:157], v[120:123]
	v_mfma_f32_16x16x32_bf16 v[116:119], v[198:201], v[154:157], v[116:119]
	v_mfma_f32_16x16x32_bf16 v[112:115], v[212:215], v[154:157], v[112:115]
	ds_read_b128 v[216:219], v137 offset:11264
	s_waitcnt lgkmcnt(4)
	v_mfma_f32_16x16x32_bf16 v[108:111], v[186:189], v[182:185], v[108:111]
	v_mfma_f32_16x16x32_bf16 v[104:107], v[194:197], v[182:185], v[104:107]
	v_mfma_f32_16x16x32_bf16 v[100:103], v[198:201], v[182:185], v[100:103]
	v_mfma_f32_16x16x32_bf16 v[96:99], v[212:215], v[182:185], v[96:99]
	ds_read_b128 v[220:223], v137 offset:13312
	s_waitcnt lgkmcnt(4)
	v_mfma_f32_16x16x32_bf16 v[92:95], v[186:189], v[158:161], v[92:95]
	v_mfma_f32_16x16x32_bf16 v[88:91], v[194:197], v[158:161], v[88:91]
	v_mfma_f32_16x16x32_bf16 v[84:87], v[198:201], v[158:161], v[84:87]
	v_mfma_f32_16x16x32_bf16 v[80:83], v[212:215], v[158:161], v[80:83]
	ds_read_b128 v[224:227], v137 offset:15360
	s_waitcnt lgkmcnt(4)
	v_mfma_f32_16x16x32_bf16 v[76:79], v[186:189], v[138:141], v[76:79]
	v_mfma_f32_16x16x32_bf16 v[72:75], v[194:197], v[138:141], v[72:75]
	v_mfma_f32_16x16x32_bf16 v[68:71], v[198:201], v[138:141], v[68:71]
	v_mfma_f32_16x16x32_bf16 v[64:67], v[212:215], v[138:141], v[64:67]
	s_waitcnt lgkmcnt(0)
	s_cmp_lg_u32 s26, 0
	s_cbranch_scc1 .Lg_rot146_ectl
	s_waitcnt vmcnt(0)
.Lg_rot146_ectl:
	s_add_i32 s11, s11, 64
	s_add_i32 s17, s17, 0x10000
	s_add_i32 s13, s13, 1
	s_cmpk_lg_i32 s11, 0x400
	s_barrier
	s_cbranch_scc1 .LBB0_146
	v_mfma_f32_16x16x32_bf16 v[60:63], v[186:189], v[190:193], v[60:63]
	v_mfma_f32_16x16x32_bf16 v[56:59], v[194:197], v[190:193], v[56:59]
	v_mfma_f32_16x16x32_bf16 v[52:55], v[198:201], v[190:193], v[52:55]
	v_mfma_f32_16x16x32_bf16 v[48:51], v[212:215], v[190:193], v[48:51]
	v_mfma_f32_16x16x32_bf16 v[44:47], v[186:189], v[216:219], v[44:47]
	v_mfma_f32_16x16x32_bf16 v[40:43], v[194:197], v[216:219], v[40:43]
	v_mfma_f32_16x16x32_bf16 v[36:39], v[198:201], v[216:219], v[36:39]
	v_mfma_f32_16x16x32_bf16 v[32:35], v[212:215], v[216:219], v[32:35]
	v_mfma_f32_16x16x32_bf16 v[28:31], v[186:189], v[220:223], v[28:31]
	v_mfma_f32_16x16x32_bf16 v[24:27], v[194:197], v[220:223], v[24:27]
	v_mfma_f32_16x16x32_bf16 v[20:23], v[198:201], v[220:223], v[20:23]
	v_mfma_f32_16x16x32_bf16 v[16:19], v[212:215], v[220:223], v[16:19]
	v_mfma_f32_16x16x32_bf16 v[12:15], v[186:189], v[224:227], v[12:15]
	v_mfma_f32_16x16x32_bf16 v[8:11], v[194:197], v[224:227], v[8:11]
	v_mfma_f32_16x16x32_bf16 v[4:7], v[198:201], v[224:227], v[4:7]
	v_mfma_f32_16x16x32_bf16 v[0:3], v[212:215], v[224:227], v[0:3]
	s_nop 7
	s_nop 1

; #define LDB_(dst, ks) _Pragma("unroll") for (int n = 0; n < 4; ++n) dst[n] = *(const bf16x8*)(sB + b_off + n * 2048 + (ks) * 1024)
; #define LDA_(dst, ks, h) _Pragma("unroll") for (int m = 0; m < 4; ++m) dst[m] = *(const bf16x8*)(sA + a_off + ((h) * 4 + m) * 2048 + (ks) * 1024)
; #define MMA_(A, B, h) _Pragma("unroll") for (int m = 0; m < 4; ++m) _Pragma("unroll") for (int n = 0; n < 4; ++n) \
;       acc[(h) * 4 + m][n] = SWAP ? MFMA16(B[n], A[m], acc[(h) * 4 + m][n]) : MFMA16(A[m], B[n], acc[(h) * 4 + m][n])
; template <int MF, int NF, bool SWAP = true>
; DI void gemm_main(f32x4 (&acc)[MF][NF], const u16* __restrict__ Ab, int lda, const u16* __restrict__ Bb, int ldb,
;                   int K, char* shm) {
;     ...
;   for (int t = 0; t < nt; ++t) {
;     const int cur = RING3 ? cur3 : (t & 1);
;     if constexpr (RING3) {
;       if (t + 2 < nt) G_STAGE(nxt3, t + 2);
;     } else {
;       if (t + 1 < nt) G_STAGE(cur ^ 1, t + 1);
;     }
;     const char* sA = shm + cur * STAGE;
;     const char* sB = sA + TILE_A;
;     if constexpr (MF == 8 && NF == 4) {
;       bf16x8 B0[4], B1[4], A0[4], A1[4], A2[4], A3[4];
;     ...
;       LDB_(B0, 0); LDA_(A0, 0, 0);
;       LDA_(A1, 0, 1); MMA_(A0, B0, 0);
;       LDB_(B1, 1); LDA_(A2, 1, 0); MMA_(A1, B0, 1);
;       LDA_(A3, 1, 1); MMA_(A2, B1, 0);
;       MMA_(A3, B1, 1);
.LBB0_244:
	s_and_b32 s18, s15, 0x10000
	v_add_u32_e32 v154, s18, v136
	v_add_u32_e32 v178, v154, v132
	ds_read_b128 v[138:141], v178 offset:32768
	ds_read_b128 v[142:145], v178 offset:34816
	ds_read_b128 v[146:149], v178 offset:36864
	ds_read_b128 v[150:153], v178 offset:38912
	v_add_u32_e32 v186, v154, v129
	ds_read_b128 v[154:157], v186
	ds_read_b128 v[158:161], v186 offset:2048
	ds_read_b128 v[162:165], v186 offset:4096
	ds_read_b128 v[166:169], v186 offset:6144
	ds_read_b128 v[170:173], v186 offset:8192
	s_cmp_gt_u32 s17, 14
	s_cbranch_scc1 .Lg_rot244_last
	s_cmp_eq_u32 s17, 0
	s_cbranch_scc1 .Lg_rot244_first
	s_cmp_lg_u32 s26, 0
	s_cbranch_scc0 .Lg_rot244_ehead
	v_mfma_f32_16x16x32_bf16 v[60:63], v[188:191], v[192:195], v[60:63]
	s_xor_b32 s19, s18, 0x10000
	v_add_u32_e32 v179, s19, v128
	v_mfma_f32_16x16x32_bf16 v[56:59], v[196:199], v[192:195], v[56:59]
	s_nop 0
	v_readfirstlane_b32 s19, v179
	s_nop 1
	s_add_u32 m0, s19, 0x0
	v_mfma_f32_16x16x32_bf16 v[52:55], v[212:215], v[192:195], v[52:55]
	global_load_lds_dwordx4 v251, s[98:99]
	s_add_u32 m0, s19, 0x2000
	v_mfma_f32_16x16x32_bf16 v[48:51], v[216:219], v[192:195], v[48:51]
	global_load_lds_dwordx4 v250, s[98:99]
	s_add_u32 m0, s19, 0x4000
	v_mfma_f32_16x16x32_bf16 v[44:47], v[188:191], v[220:223], v[44:47]
	global_load_lds_dwordx4 v249, s[98:99]
	s_add_u32 m0, s19, 0x6000
	v_mfma_f32_16x16x32_bf16 v[40:43], v[196:199], v[220:223], v[40:43]
	global_load_lds_dwordx4 v248, s[98:99]
	s_add_u32 m0, s19, 0x8000
	v_mfma_f32_16x16x32_bf16 v[36:39], v[212:215], v[220:223], v[36:39]
	global_load_lds_dwordx4 v247, s[100:101]
	s_add_u32 m0, s19, 0xa000
	v_mfma_f32_16x16x32_bf16 v[32:35], v[216:219], v[220:223], v[32:35]
	global_load_lds_dwordx4 v246, s[100:101]
	s_add_u32 m0, s19, 0xc000
	v_mfma_f32_16x16x32_bf16 v[28:31], v[188:191], v[224:227], v[28:31]
	global_load_lds_dwordx4 v245, s[100:101]
	s_add_u32 m0, s19, 0xe000
	v_mfma_f32_16x16x32_bf16 v[24:27], v[196:199], v[224:227], v[24:27]
	global_load_lds_dwordx4 v244, s[100:101]
	v_mfma_f32_16x16x32_bf16 v[20:23], v[212:215], v[224:227], v[20:23]
	s_add_u32 s98, s98, 0x80
	s_addc_u32 s99, s99, 0
	s_add_u32 s100, s100, 0x80
	s_addc_u32 s101, s101, 0
	v_mfma_f32_16x16x32_bf16 v[16:19], v[216:219], v[224:227], v[16:19]
	v_mfma_f32_16x16x32_bf16 v[12:15], v[188:191], v[228:231], v[12:15]
	v_mfma_f32_16x16x32_bf16 v[8:11], v[196:199], v[228:231], v[8:11]
	v_mfma_f32_16x16x32_bf16 v[4:7], v[212:215], v[228:231], v[4:7]
	v_mfma_f32_16x16x32_bf16 v[0:3], v[216:219], v[228:231], v[0:3]
	s_branch .Lg_rot244_main
.Lg_rot244_ehead:
	v_mfma_f32_16x16x32_bf16 v[60:63], v[188:191], v[192:195], v[60:63]
	s_add_u32 s98, s98, 0x80
	s_addc_u32 s99, s99, 0
	s_add_u32 s100, s100, 0x80
	s_addc_u32 s101, s101, 0
	v_mfma_f32_16x16x32_bf16 v[56:59], v[196:199], v[192:195], v[56:59]
	v_mfma_f32_16x16x32_bf16 v[52:55], v[212:215], v[192:195], v[52:55]
	v_mfma_f32_16x16x32_bf16 v[48:51], v[216:219], v[192:195], v[48:51]
	v_mfma_f32_16x16x32_bf16 v[44:47], v[188:191], v[220:223], v[44:47]
	v_mfma_f32_16x16x32_bf16 v[40:43], v[196:199], v[220:223], v[40:43]
	v_mfma_f32_16x16x32_bf16 v[36:39], v[212:215], v[220:223], v[36:39]
	v_mfma_f32_16x16x32_bf16 v[32:35], v[216:219], v[220:223], v[32:35]
	v_mfma_f32_16x16x32_bf16 v[28:31], v[188:191], v[224:227], v[28:31]
	v_mfma_f32_16x16x32_bf16 v[24:27], v[196:199], v[224:227], v[24:27]
	v_mfma_f32_16x16x32_bf16 v[20:23], v[212:215], v[224:227], v[20:23]
	v_mfma_f32_16x16x32_bf16 v[16:19], v[216:219], v[224:227], v[16:19]
	v_mfma_f32_16x16x32_bf16 v[12:15], v[188:191], v[228:231], v[12:15]
	v_mfma_f32_16x16x32_bf16 v[8:11], v[196:199], v[228:231], v[8:11]
	v_mfma_f32_16x16x32_bf16 v[4:7], v[212:215], v[228:231], v[4:7]
	v_mfma_f32_16x16x32_bf16 v[0:3], v[216:219], v[228:231], v[0:3]
	s_branch .Lg_rot244_main
.Lg_rot244_first:
	v_add_u32_e32 v174, s16, v137
	s_xor_b32 s19, s18, 0x10000
	v_add_u32_e32 v176, 64, v174
	v_add_u32_e32 v179, s19, v128
	v_ashrrev_i32_e32 v177, 31, v176
	v_lshlrev_b64 v[176:177], 1, v[176:177]
	v_readfirstlane_b32 s19, v179
	v_lshl_add_u64 v[180:181], s[6:7], 0, v[176:177]
	s_mov_b32 m0, s19
	v_add_u32_e32 v182, 0x2000, v179
	global_load_lds_dwordx4 v[180:181], off
	v_subrev_u32_e32 v251, s6, v180
	v_add_u32_e32 v180, 0x10040, v174
	v_ashrrev_i32_e32 v181, 31, v180
	v_lshlrev_b64 v[180:181], 1, v[180:181]
	v_readfirstlane_b32 s19, v182
	v_lshl_add_u64 v[184:185], s[6:7], 0, v[180:181]
	s_mov_b32 m0, s19
	v_add_u32_e32 v175, 0x4000, v179
	global_load_lds_dwordx4 v[184:185], off
	v_subrev_u32_e32 v250, s6, v184
	v_add_u32_e32 v184, 0x20040, v174
	v_ashrrev_i32_e32 v185, 31, v184
	v_lshlrev_b64 v[184:185], 1, v[184:185]
	v_readfirstlane_b32 s19, v175
	v_lshl_add_u64 v[182:183], s[6:7], 0, v[184:185]
	s_mov_b32 m0, s19
	v_add_u32_e32 v187, 0x6000, v179
	global_load_lds_dwordx4 v[182:183], off
	v_subrev_u32_e32 v249, s6, v182
	v_add_u32_e32 v182, 0x30040, v174
	v_ashrrev_i32_e32 v183, 31, v182
	v_lshlrev_b64 v[182:183], 1, v[182:183]
	v_readfirstlane_b32 s19, v187
	v_lshl_add_u64 v[174:175], s[6:7], 0, v[182:183]
	s_mov_b32 m0, s19
	v_lshl_add_u64 v[176:177], s[0:1], 0, v[176:177]
	global_load_lds_dwordx4 v[174:175], off
	v_subrev_u32_e32 v248, s6, v174
	v_add_u32_e32 v174, 0x8000, v179
	s_nop 0
	v_readfirstlane_b32 s19, v174
	s_mov_b32 m0, s19
	s_nop 0
	global_load_lds_dwordx4 v[176:177], off
	v_subrev_u32_e32 v247, s0, v176
	v_lshl_add_u64 v[176:177], s[0:1], 0, v[180:181]
	v_add_u32_e32 v180, 0xa000, v179
	s_nop 0
	v_readfirstlane_b32 s19, v180
	v_add_u32_e32 v180, 0xc000, v179
	s_mov_b32 m0, s19
	v_readfirstlane_b32 s19, v180
	v_add_u32_e32 v180, 0xe000, v179
	global_load_lds_dwordx4 v[176:177], off
	v_subrev_u32_e32 v246, s0, v176
	v_lshl_add_u64 v[176:177], s[0:1], 0, v[184:185]
	s_mov_b32 m0, s19
	v_readfirstlane_b32 s19, v180
	global_load_lds_dwordx4 v[176:177], off
	v_subrev_u32_e32 v245, s0, v176
	v_lshl_add_u64 v[176:177], s[0:1], 0, v[182:183]
	s_mov_b32 m0, s19
	s_nop 0
	global_load_lds_dwordx4 v[176:177], off
	v_subrev_u32_e32 v244, s0, v176
	s_add_u32 s98, s6, 0x80
	s_addc_u32 s99, s7, 0
	s_add_u32 s100, s0, 0x80
	s_addc_u32 s101, s1, 0
	v_readfirstlane_b32 s26, v179
	s_bfe_u32 s26, s26, 0x1000a
	s_branch .Lg_rot244_main

; #define LDB_(dst, ks) _Pragma("unroll") for (int n = 0; n < 4; ++n) dst[n] = *(const bf16x8*)(sB + b_off + n * 2048 + (ks) * 1024)
; #define LDA_(dst, ks, h) _Pragma("unroll") for (int m = 0; m < 4; ++m) dst[m] = *(const bf16x8*)(sA + a_off + ((h) * 4 + m) * 2048 + (ks) * 1024)
; #define MMA_(A, B, h) _Pragma("unroll") for (int m = 0; m < 4; ++m) _Pragma("unroll") for (int n = 0; n < 4; ++n) \
;       acc[(h) * 4 + m][n] = SWAP ? MFMA16(B[n], A[m], acc[(h) * 4 + m][n]) : MFMA16(A[m], B[n], acc[(h) * 4 + m][n])
; template <int MF, int NF, bool SWAP = true>
; DI void gemm_main(f32x4 (&acc)[MF][NF], const u16* __restrict__ Ab, int lda, const u16* __restrict__ Bb, int ldb,
;                   int K, char* shm) {
;     ...
;     if constexpr (MF == 8 && NF == 4) {
;       bf16x8 B0[4], B1[4], A0[4], A1[4], A2[4], A3[4];
;     ...
;       LDB_(B0, 0); LDA_(A0, 0, 0);
;       LDA_(A1, 0, 1); MMA_(A0, B0, 0);
;       LDB_(B1, 1); LDA_(A2, 1, 0); MMA_(A1, B0, 1);
;       LDA_(A3, 1, 1); MMA_(A2, B1, 0);
;       MMA_(A3, B1, 1);
.Lg_rot244_main:
	s_waitcnt lgkmcnt(4)
	v_mfma_f32_16x16x32_bf16 v[124:127], v[138:141], v[154:157], v[124:127]
	v_mfma_f32_16x16x32_bf16 v[120:123], v[142:145], v[154:157], v[120:123]
	v_mfma_f32_16x16x32_bf16 v[116:119], v[146:149], v[154:157], v[116:119]
	v_mfma_f32_16x16x32_bf16 v[112:115], v[150:153], v[154:157], v[112:115]
	ds_read_b128 v[154:157], v186 offset:10240
	s_waitcnt lgkmcnt(4)
	v_mfma_f32_16x16x32_bf16 v[108:111], v[138:141], v[158:161], v[108:111]
	v_mfma_f32_16x16x32_bf16 v[104:107], v[142:145], v[158:161], v[104:107]
	v_mfma_f32_16x16x32_bf16 v[100:103], v[146:149], v[158:161], v[100:103]
	v_mfma_f32_16x16x32_bf16 v[96:99], v[150:153], v[158:161], v[96:99]
	ds_read_b128 v[158:161], v186 offset:12288
	s_waitcnt lgkmcnt(4)
	v_mfma_f32_16x16x32_bf16 v[92:95], v[138:141], v[162:165], v[92:95]
	v_mfma_f32_16x16x32_bf16 v[88:91], v[142:145], v[162:165], v[88:91]
	v_mfma_f32_16x16x32_bf16 v[84:87], v[146:149], v[162:165], v[84:87]
	v_mfma_f32_16x16x32_bf16 v[80:83], v[150:153], v[162:165], v[80:83]
	ds_read_b128 v[162:165], v186 offset:14336
	s_waitcnt lgkmcnt(4)
	v_mfma_f32_16x16x32_bf16 v[76:79], v[138:141], v[166:169], v[76:79]
	v_mfma_f32_16x16x32_bf16 v[72:75], v[142:145], v[166:169], v[72:75]
	v_mfma_f32_16x16x32_bf16 v[68:71], v[146:149], v[166:169], v[68:71]
	v_mfma_f32_16x16x32_bf16 v[64:67], v[150:153], v[166:169], v[64:67]
	s_waitcnt lgkmcnt(0)
	s_cmp_eq_u32 s26, 0
	s_cbranch_scc1 .Lg_rot244_mbar
	s_cmp_gt_u32 s17, 14
	s_cbranch_scc1 .Lg_rot244_mw0
	s_waitcnt vmcnt(8)
	s_branch .Lg_rot244_mbar

; #define LDB_(dst, ks) _Pragma("unroll") for (int n = 0; n < 4; ++n) dst[n] = *(const bf16x8*)(sB + b_off + n * 2048 + (ks) * 1024)
; #define LDA_(dst, ks, h) _Pragma("unroll") for (int m = 0; m < 4; ++m) dst[m] = *(const bf16x8*)(sA + a_off + ((h) * 4 + m) * 2048 + (ks) * 1024)
; #define MMA_(A, B, h) _Pragma("unroll") for (int m = 0; m < 4; ++m) _Pragma("unroll") for (int n = 0; n < 4; ++n) \
;       acc[(h) * 4 + m][n] = SWAP ? MFMA16(B[n], A[m], acc[(h) * 4 + m][n]) : MFMA16(A[m], B[n], acc[(h) * 4 + m][n])
; template <int MF, int NF, bool SWAP = true>
; DI void gemm_main(f32x4 (&acc)[MF][NF], const u16* __restrict__ Ab, int lda, const u16* __restrict__ Bb, int ldb,
;                   int K, char* shm) {
;     ...
;   for (int t = 0; t < nt; ++t) {
;     const int cur = RING3 ? cur3 : (t & 1);
;     if constexpr (RING3) {
;       if (t + 2 < nt) G_STAGE(nxt3, t + 2);
;     } else {
;       if (t + 1 < nt) G_STAGE(cur ^ 1, t + 1);
;     }
;     const char* sA = shm + cur * STAGE;
;     const char* sB = sA + TILE_A;
;     if constexpr (MF == 8 && NF == 4) {
;       bf16x8 B0[4], B1[4], A0[4], A1[4], A2[4], A3[4];
;     ...
;       LDB_(B0, 0); LDA_(A0, 0, 0);
;       LDA_(A1, 0, 1); MMA_(A0, B0, 0);
;       LDB_(B1, 1); LDA_(A2, 1, 0); MMA_(A1, B0, 1);
;       LDA_(A3, 1, 1); MMA_(A2, B1, 0);
;       MMA_(A3, B1, 1);
.Lg_rot244_mbar:
	s_barrier
	s_cmp_lg_u32 s26, 0
	s_cbranch_scc1 .Lg_rot244_bplain
	s_cmp_gt_u32 s17, 13
	s_cbranch_scc1 .Lg_rot244_bplain
	ds_read_b128 v[188:191], v178 offset:33792
	v_mfma_f32_16x16x32_bf16 v[60:63], v[138:141], v[170:173], v[60:63]
	v_add_u32_e32 v255, s18, v128
	s_nop 0
	v_readfirstlane_b32 s19, v255
	s_nop 1
	s_add_u32 m0, s19, 0x0
	v_mfma_f32_16x16x32_bf16 v[56:59], v[142:145], v[170:173], v[56:59]
	global_load_lds_dwordx4 v251, s[98:99]
	s_add_u32 m0, s19, 0x2000
	ds_read_b128 v[196:199], v178 offset:35840
	v_mfma_f32_16x16x32_bf16 v[52:55], v[146:149], v[170:173], v[52:55]
	global_load_lds_dwordx4 v250, s[98:99]
	s_add_u32 m0, s19, 0x4000
	v_mfma_f32_16x16x32_bf16 v[48:51], v[150:153], v[170:173], v[48:51]
	global_load_lds_dwordx4 v249, s[98:99]
	s_add_u32 m0, s19, 0x6000
	ds_read_b128 v[212:215], v178 offset:37888
	v_mfma_f32_16x16x32_bf16 v[44:47], v[138:141], v[154:157], v[44:47]
	global_load_lds_dwordx4 v248, s[98:99]
	s_add_u32 m0, s19, 0x8000
	v_mfma_f32_16x16x32_bf16 v[40:43], v[142:145], v[154:157], v[40:43]
	global_load_lds_dwordx4 v247, s[100:101]
	s_add_u32 m0, s19, 0xa000
	ds_read_b128 v[216:219], v178 offset:39936
	v_mfma_f32_16x16x32_bf16 v[36:39], v[146:149], v[154:157], v[36:39]
	global_load_lds_dwordx4 v246, s[100:101]
	s_add_u32 m0, s19, 0xc000
	v_mfma_f32_16x16x32_bf16 v[32:35], v[150:153], v[154:157], v[32:35]
	global_load_lds_dwordx4 v245, s[100:101]
	s_add_u32 m0, s19, 0xe000
	ds_read_b128 v[154:157], v186 offset:1024
	v_mfma_f32_16x16x32_bf16 v[28:31], v[138:141], v[158:161], v[28:31]
	global_load_lds_dwordx4 v244, s[100:101]
	v_mfma_f32_16x16x32_bf16 v[24:27], v[142:145], v[158:161], v[24:27]
	ds_read_b128 v[182:185], v186 offset:3072
	v_mfma_f32_16x16x32_bf16 v[20:23], v[146:149], v[158:161], v[20:23]
	v_mfma_f32_16x16x32_bf16 v[16:19], v[150:153], v[158:161], v[16:19]
	ds_read_b128 v[158:161], v186 offset:5120
	v_mfma_f32_16x16x32_bf16 v[12:15], v[138:141], v[162:165], v[12:15]
	v_mfma_f32_16x16x32_bf16 v[8:11], v[142:145], v[162:165], v[8:11]
	ds_read_b128 v[138:141], v186 offset:7168
	v_mfma_f32_16x16x32_bf16 v[4:7], v[146:149], v[162:165], v[4:7]
	v_mfma_f32_16x16x32_bf16 v[0:3], v[150:153], v[162:165], v[0:3]
	ds_read_b128 v[192:195], v186 offset:9216
	s_waitcnt lgkmcnt(4)
	v_mfma_f32_16x16x32_bf16 v[124:127], v[188:191], v[154:157], v[124:127]
	v_mfma_f32_16x16x32_bf16 v[120:123], v[196:199], v[154:157], v[120:123]
	v_mfma_f32_16x16x32_bf16 v[116:119], v[212:215], v[154:157], v[116:119]
	v_mfma_f32_16x16x32_bf16 v[112:115], v[216:219], v[154:157], v[112:115]
	ds_read_b128 v[220:223], v186 offset:11264
	s_waitcnt lgkmcnt(4)
	v_mfma_f32_16x16x32_bf16 v[108:111], v[188:191], v[182:185], v[108:111]
	v_mfma_f32_16x16x32_bf16 v[104:107], v[196:199], v[182:185], v[104:107]
	v_mfma_f32_16x16x32_bf16 v[100:103], v[212:215], v[182:185], v[100:103]
	v_mfma_f32_16x16x32_bf16 v[96:99], v[216:219], v[182:185], v[96:99]
	ds_read_b128 v[224:227], v186 offset:13312
	s_waitcnt lgkmcnt(4)
	v_mfma_f32_16x16x32_bf16 v[92:95], v[188:191], v[158:161], v[92:95]
	v_mfma_f32_16x16x32_bf16 v[88:91], v[196:199], v[158:161], v[88:91]
	v_mfma_f32_16x16x32_bf16 v[84:87], v[212:215], v[158:161], v[84:87]
	v_mfma_f32_16x16x32_bf16 v[80:83], v[216:219], v[158:161], v[80:83]
	ds_read_b128 v[228:231], v186 offset:15360
	s_waitcnt lgkmcnt(4)
	v_mfma_f32_16x16x32_bf16 v[76:79], v[188:191], v[138:141], v[76:79]
	v_mfma_f32_16x16x32_bf16 v[72:75], v[196:199], v[138:141], v[72:75]
	v_mfma_f32_16x16x32_bf16 v[68:71], v[212:215], v[138:141], v[68:71]
	v_mfma_f32_16x16x32_bf16 v[64:67], v[216:219], v[138:141], v[64:67]
	s_waitcnt lgkmcnt(0)
	s_waitcnt vmcnt(8)
	s_branch .Lg_rot244_ectl
; #define LDB_(dst, ks) _Pragma("unroll") for (int n = 0; n < 4; ++n) dst[n] = *(const bf16x8*)(sB + b_off + n * 2048 + (ks) * 1024)
; #define LDA_(dst, ks, h) _Pragma("unroll") for (int m = 0; m < 4; ++m) dst[m] = *(const bf16x8*)(sA + a_off + ((h) * 4 + m) * 2048 + (ks) * 1024)
; #define MMA_(A, B, h) _Pragma("unroll") for (int m = 0; m < 4; ++m) _Pragma("unroll") for (int n = 0; n < 4; ++n) \
;       acc[(h) * 4 + m][n] = SWAP ? MFMA16(B[n], A[m], acc[(h) * 4 + m][n]) : MFMA16(A[m], B[n], acc[(h) * 4 + m][n])
; template <int MF, int NF, bool SWAP = true>
; DI void gemm_main(f32x4 (&acc)[MF][NF], const u16* __restrict__ Ab, int lda, const u16* __restrict__ Bb, int ldb,
;                   int K, char* shm) {
;     ...
;     if constexpr (MF == 8 && NF == 4) {
;       bf16x8 B0[4], B1[4], A0[4], A1[4], A2[4], A3[4];
;     ...
;       LDB_(B0, 0); LDA_(A0, 0, 0);
;       LDA_(A1, 0, 1); MMA_(A0, B0, 0);
;       LDB_(B1, 1); LDA_(A2, 1, 0); MMA_(A1, B0, 1);
;       LDA_(A3, 1, 1); MMA_(A2, B1, 0);
;       MMA_(A3, B1, 1);
;     ...
;     if constexpr (RING3) {
;       if (t + 2 < nt) asm volatile("s_waitcnt vmcnt(6)" ::: "memory");
;       else asm volatile("s_waitcnt vmcnt(0)" ::: "memory");
;       asm volatile("s_waitcnt lgkmcnt(0)" ::: "memory");
;       __builtin_amdgcn_s_barrier();
;       cur3 = (cur3 == 2) ? 0 : cur3 + 1;
;       nxt3 = (nxt3 == 2) ? 0 : nxt3 + 1;
;     } else {
;       asm volatile("s_waitcnt vmcnt(0)" ::: "memory");
;       __syncthreads();
;     }
;   }
.Lg_rot244_bplain:
	ds_read_b128 v[188:191], v178 offset:33792
	v_mfma_f32_16x16x32_bf16 v[60:63], v[138:141], v[170:173], v[60:63]
	v_mfma_f32_16x16x32_bf16 v[56:59], v[142:145], v[170:173], v[56:59]
	ds_read_b128 v[196:199], v178 offset:35840
	v_mfma_f32_16x16x32_bf16 v[52:55], v[146:149], v[170:173], v[52:55]
	v_mfma_f32_16x16x32_bf16 v[48:51], v[150:153], v[170:173], v[48:51]
	ds_read_b128 v[212:215], v178 offset:37888
	v_mfma_f32_16x16x32_bf16 v[44:47], v[138:141], v[154:157], v[44:47]
	v_mfma_f32_16x16x32_bf16 v[40:43], v[142:145], v[154:157], v[40:43]
	ds_read_b128 v[216:219], v178 offset:39936
	v_mfma_f32_16x16x32_bf16 v[36:39], v[146:149], v[154:157], v[36:39]
	v_mfma_f32_16x16x32_bf16 v[32:35], v[150:153], v[154:157], v[32:35]
	ds_read_b128 v[154:157], v186 offset:1024
	v_mfma_f32_16x16x32_bf16 v[28:31], v[138:141], v[158:161], v[28:31]
	v_mfma_f32_16x16x32_bf16 v[24:27], v[142:145], v[158:161], v[24:27]
	ds_read_b128 v[182:185], v186 offset:3072
	v_mfma_f32_16x16x32_bf16 v[20:23], v[146:149], v[158:161], v[20:23]
	v_mfma_f32_16x16x32_bf16 v[16:19], v[150:153], v[158:161], v[16:19]
	ds_read_b128 v[158:161], v186 offset:5120
	v_mfma_f32_16x16x32_bf16 v[12:15], v[138:141], v[162:165], v[12:15]
	v_mfma_f32_16x16x32_bf16 v[8:11], v[142:145], v[162:165], v[8:11]
	ds_read_b128 v[138:141], v186 offset:7168
	v_mfma_f32_16x16x32_bf16 v[4:7], v[146:149], v[162:165], v[4:7]
	v_mfma_f32_16x16x32_bf16 v[0:3], v[150:153], v[162:165], v[0:3]
	ds_read_b128 v[192:195], v186 offset:9216
	s_waitcnt lgkmcnt(4)
	v_mfma_f32_16x16x32_bf16 v[124:127], v[188:191], v[154:157], v[124:127]
	v_mfma_f32_16x16x32_bf16 v[120:123], v[196:199], v[154:157], v[120:123]
	v_mfma_f32_16x16x32_bf16 v[116:119], v[212:215], v[154:157], v[116:119]
	v_mfma_f32_16x16x32_bf16 v[112:115], v[216:219], v[154:157], v[112:115]
	ds_read_b128 v[220:223], v186 offset:11264
	s_waitcnt lgkmcnt(4)
	v_mfma_f32_16x16x32_bf16 v[108:111], v[188:191], v[182:185], v[108:111]
	v_mfma_f32_16x16x32_bf16 v[104:107], v[196:199], v[182:185], v[104:107]
	v_mfma_f32_16x16x32_bf16 v[100:103], v[212:215], v[182:185], v[100:103]
	v_mfma_f32_16x16x32_bf16 v[96:99], v[216:219], v[182:185], v[96:99]
	ds_read_b128 v[224:227], v186 offset:13312
	s_waitcnt lgkmcnt(4)
	v_mfma_f32_16x16x32_bf16 v[92:95], v[188:191], v[158:161], v[92:95]
	v_mfma_f32_16x16x32_bf16 v[88:91], v[196:199], v[158:161], v[88:91]
	v_mfma_f32_16x16x32_bf16 v[84:87], v[212:215], v[158:161], v[84:87]
	v_mfma_f32_16x16x32_bf16 v[80:83], v[216:219], v[158:161], v[80:83]
	ds_read_b128 v[228:231], v186 offset:15360
	s_waitcnt lgkmcnt(4)
	v_mfma_f32_16x16x32_bf16 v[76:79], v[188:191], v[138:141], v[76:79]
	v_mfma_f32_16x16x32_bf16 v[72:75], v[196:199], v[138:141], v[72:75]
	v_mfma_f32_16x16x32_bf16 v[68:71], v[212:215], v[138:141], v[68:71]
	v_mfma_f32_16x16x32_bf16 v[64:67], v[216:219], v[138:141], v[64:67]
	s_waitcnt lgkmcnt(0)
	s_cmp_lg_u32 s26, 0
	s_cbranch_scc1 .Lg_rot244_ectl
	s_waitcnt vmcnt(0)
.Lg_rot244_ectl:
	s_add_i32 s16, s16, 64
	s_add_i32 s15, s15, 0x10000
	s_add_i32 s17, s17, 1
	s_cmpk_lg_i32 s16, 0x400
	s_barrier
	s_cbranch_scc1 .LBB0_244
	v_mfma_f32_16x16x32_bf16 v[60:63], v[188:191], v[192:195], v[60:63]
	v_mfma_f32_16x16x32_bf16 v[56:59], v[196:199], v[192:195], v[56:59]
	v_mfma_f32_16x16x32_bf16 v[52:55], v[212:215], v[192:195], v[52:55]
	v_mfma_f32_16x16x32_bf16 v[48:51], v[216:219], v[192:195], v[48:51]
	v_mfma_f32_16x16x32_bf16 v[44:47], v[188:191], v[220:223], v[44:47]
	v_mfma_f32_16x16x32_bf16 v[40:43], v[196:199], v[220:223], v[40:43]
	v_mfma_f32_16x16x32_bf16 v[36:39], v[212:215], v[220:223], v[36:39]
	v_mfma_f32_16x16x32_bf16 v[32:35], v[216:219], v[220:223], v[32:35]
	v_mfma_f32_16x16x32_bf16 v[28:31], v[188:191], v[224:227], v[28:31]
	v_mfma_f32_16x16x32_bf16 v[24:27], v[196:199], v[224:227], v[24:27]
	v_mfma_f32_16x16x32_bf16 v[20:23], v[212:215], v[224:227], v[20:23]
	v_mfma_f32_16x16x32_bf16 v[16:19], v[216:219], v[224:227], v[16:19]
	v_mfma_f32_16x16x32_bf16 v[12:15], v[188:191], v[228:231], v[12:15]
	v_mfma_f32_16x16x32_bf16 v[8:11], v[196:199], v[228:231], v[8:11]
	v_mfma_f32_16x16x32_bf16 v[4:7], v[212:215], v[228:231], v[4:7]
	v_mfma_f32_16x16x32_bf16 v[0:3], v[216:219], v[228:231], v[0:3]
	s_nop 7
	s_nop 1

; #define LDB_(dst, ks) _Pragma("unroll") for (int n = 0; n < 4; ++n) dst[n] = *(const bf16x8*)(sB + b_off + n * 2048 + (ks) * 1024)
; #define LDA_(dst, ks, h) _Pragma("unroll") for (int m = 0; m < 4; ++m) dst[m] = *(const bf16x8*)(sA + a_off + ((h) * 4 + m) * 2048 + (ks) * 1024)
; #define MMA_(A, B, h) _Pragma("unroll") for (int m = 0; m < 4; ++m) _Pragma("unroll") for (int n = 0; n < 4; ++n) \
;       acc[(h) * 4 + m][n] = SWAP ? MFMA16(B[n], A[m], acc[(h) * 4 + m][n]) : MFMA16(A[m], B[n], acc[(h) * 4 + m][n])
; template <int MF, int NF, bool SWAP = true>
; DI void gemm_main(f32x4 (&acc)[MF][NF], const u16* __restrict__ Ab, int lda, const u16* __restrict__ Bb, int ldb,
;                   int K, char* shm) {
;     ...
;   for (int t = 0; t < nt; ++t) {
;     const int cur = RING3 ? cur3 : (t & 1);
;     if constexpr (RING3) {
;       if (t + 2 < nt) G_STAGE(nxt3, t + 2);
;     } else {
;       if (t + 1 < nt) G_STAGE(cur ^ 1, t + 1);
;     }
;     const char* sA = shm + cur * STAGE;
;     const char* sB = sA + TILE_A;
;     if constexpr (MF == 8 && NF == 4) {
;       bf16x8 B0[4], B1[4], A0[4], A1[4], A2[4], A3[4];
;     ...
;       LDB_(B0, 0); LDA_(A0, 0, 0);
;       LDA_(A1, 0, 1); MMA_(A0, B0, 0);
;       LDB_(B1, 1); LDA_(A2, 1, 0); MMA_(A1, B0, 1);
;       LDA_(A3, 1, 1); MMA_(A2, B1, 0);
;       MMA_(A3, B1, 1);
.LBB0_314:
	s_and_b32 s16, s5, 0x10000
	v_add_u32_e32 v138, s16, v136
	v_add_u32_e32 v186, v138, v129
	v_add_u32_e32 v178, v138, v132
	ds_read_b128 v[138:141], v186
	ds_read_b128 v[158:161], v186 offset:2048
	ds_read_b128 v[142:145], v178 offset:32768
	ds_read_b128 v[146:149], v178 offset:34816
	ds_read_b128 v[150:153], v178 offset:36864
	ds_read_b128 v[154:157], v178 offset:38912
	ds_read_b128 v[162:165], v186 offset:4096
	ds_read_b128 v[166:169], v186 offset:6144
	ds_read_b128 v[170:173], v186 offset:8192
	s_cmp_gt_u32 s15, 14
	s_cbranch_scc1 .Lg_rot314_last
	s_cmp_eq_u32 s15, 0
	s_cbranch_scc1 .Lg_rot314_first
	s_cmp_lg_u32 s26, 0
	s_cbranch_scc0 .Lg_rot314_ehead
	v_mfma_f32_16x16x32_bf16 v[60:63], v[188:191], v[192:195], v[60:63]
	s_xor_b32 s17, s16, 0x10000
	v_add_u32_e32 v179, s17, v128
	v_mfma_f32_16x16x32_bf16 v[56:59], v[188:191], v[196:199], v[56:59]
	s_nop 0
	v_readfirstlane_b32 s17, v179
	s_nop 1
	s_add_u32 m0, s17, 0x0
	v_mfma_f32_16x16x32_bf16 v[52:55], v[188:191], v[212:215], v[52:55]
	global_load_lds_dwordx4 v251, s[98:99]
	s_add_u32 m0, s17, 0x2000
	v_mfma_f32_16x16x32_bf16 v[48:51], v[188:191], v[216:219], v[48:51]
	global_load_lds_dwordx4 v250, s[98:99]
	s_add_u32 m0, s17, 0x4000
	v_mfma_f32_16x16x32_bf16 v[44:47], v[220:223], v[192:195], v[44:47]
	global_load_lds_dwordx4 v249, s[98:99]
	s_add_u32 m0, s17, 0x6000
	v_mfma_f32_16x16x32_bf16 v[40:43], v[220:223], v[196:199], v[40:43]
	global_load_lds_dwordx4 v248, s[98:99]
	s_add_u32 m0, s17, 0x8000
	v_mfma_f32_16x16x32_bf16 v[36:39], v[220:223], v[212:215], v[36:39]
	global_load_lds_dwordx4 v247, s[100:101]
	s_add_u32 m0, s17, 0xa000
	v_mfma_f32_16x16x32_bf16 v[32:35], v[220:223], v[216:219], v[32:35]
	global_load_lds_dwordx4 v246, s[100:101]
	s_add_u32 m0, s17, 0xc000
	v_mfma_f32_16x16x32_bf16 v[28:31], v[224:227], v[192:195], v[28:31]
	global_load_lds_dwordx4 v245, s[100:101]
	s_add_u32 m0, s17, 0xe000
	v_mfma_f32_16x16x32_bf16 v[24:27], v[224:227], v[196:199], v[24:27]
	global_load_lds_dwordx4 v244, s[100:101]
	v_mfma_f32_16x16x32_bf16 v[20:23], v[224:227], v[212:215], v[20:23]
	s_add_u32 s98, s98, 0x80
	s_addc_u32 s99, s99, 0
	s_add_u32 s100, s100, 0x80
	s_addc_u32 s101, s101, 0
	v_mfma_f32_16x16x32_bf16 v[16:19], v[224:227], v[216:219], v[16:19]
	v_mfma_f32_16x16x32_bf16 v[12:15], v[228:231], v[192:195], v[12:15]
	v_mfma_f32_16x16x32_bf16 v[4:7], v[228:231], v[196:199], v[4:7]
	v_mfma_f32_16x16x32_bf16 v[0:3], v[228:231], v[212:215], v[0:3]
	v_mfma_f32_16x16x32_bf16 v[8:11], v[228:231], v[216:219], v[8:11]
	s_branch .Lg_rot314_main
.Lg_rot314_ehead:
	v_mfma_f32_16x16x32_bf16 v[60:63], v[188:191], v[192:195], v[60:63]
	s_add_u32 s98, s98, 0x80
	s_addc_u32 s99, s99, 0
	s_add_u32 s100, s100, 0x80
	s_addc_u32 s101, s101, 0
	v_mfma_f32_16x16x32_bf16 v[56:59], v[188:191], v[196:199], v[56:59]
	v_mfma_f32_16x16x32_bf16 v[52:55], v[188:191], v[212:215], v[52:55]
	v_mfma_f32_16x16x32_bf16 v[48:51], v[188:191], v[216:219], v[48:51]
	v_mfma_f32_16x16x32_bf16 v[44:47], v[220:223], v[192:195], v[44:47]
	v_mfma_f32_16x16x32_bf16 v[40:43], v[220:223], v[196:199], v[40:43]
	v_mfma_f32_16x16x32_bf16 v[36:39], v[220:223], v[212:215], v[36:39]
	v_mfma_f32_16x16x32_bf16 v[32:35], v[220:223], v[216:219], v[32:35]
	v_mfma_f32_16x16x32_bf16 v[28:31], v[224:227], v[192:195], v[28:31]
	v_mfma_f32_16x16x32_bf16 v[24:27], v[224:227], v[196:199], v[24:27]
	v_mfma_f32_16x16x32_bf16 v[20:23], v[224:227], v[212:215], v[20:23]
	v_mfma_f32_16x16x32_bf16 v[16:19], v[224:227], v[216:219], v[16:19]
	v_mfma_f32_16x16x32_bf16 v[12:15], v[228:231], v[192:195], v[12:15]
	v_mfma_f32_16x16x32_bf16 v[4:7], v[228:231], v[196:199], v[4:7]
	v_mfma_f32_16x16x32_bf16 v[0:3], v[228:231], v[212:215], v[0:3]
	v_mfma_f32_16x16x32_bf16 v[8:11], v[228:231], v[216:219], v[8:11]
	s_branch .Lg_rot314_main
.Lg_rot314_first:
	v_add_u32_e32 v174, s13, v137
	s_xor_b32 s17, s16, 0x10000
	v_add_u32_e32 v176, 64, v174
	v_add_u32_e32 v179, s17, v128
	v_ashrrev_i32_e32 v177, 31, v176
	v_lshlrev_b64 v[176:177], 1, v[176:177]
	v_readfirstlane_b32 s17, v179
	v_lshl_add_u64 v[180:181], s[6:7], 0, v[176:177]
	s_mov_b32 m0, s17
	v_add_u32_e32 v182, 0x2000, v179
	global_load_lds_dwordx4 v[180:181], off
	v_subrev_u32_e32 v251, s6, v180
	v_add_u32_e32 v180, 0x10040, v174
	v_ashrrev_i32_e32 v181, 31, v180
	v_lshlrev_b64 v[180:181], 1, v[180:181]
	v_readfirstlane_b32 s17, v182
	v_lshl_add_u64 v[184:185], s[6:7], 0, v[180:181]
	s_mov_b32 m0, s17
	v_add_u32_e32 v175, 0x4000, v179
	global_load_lds_dwordx4 v[184:185], off
	v_subrev_u32_e32 v250, s6, v184
	v_add_u32_e32 v184, 0x20040, v174
	v_ashrrev_i32_e32 v185, 31, v184
	v_lshlrev_b64 v[184:185], 1, v[184:185]
	v_readfirstlane_b32 s17, v175
	v_lshl_add_u64 v[182:183], s[6:7], 0, v[184:185]
	s_mov_b32 m0, s17
	v_add_u32_e32 v187, 0x6000, v179
	global_load_lds_dwordx4 v[182:183], off
	v_subrev_u32_e32 v249, s6, v182
	v_add_u32_e32 v182, 0x30040, v174
	v_ashrrev_i32_e32 v183, 31, v182
	v_lshlrev_b64 v[182:183], 1, v[182:183]
	v_readfirstlane_b32 s17, v187
	v_lshl_add_u64 v[174:175], s[6:7], 0, v[182:183]
	s_mov_b32 m0, s17
	v_lshl_add_u64 v[176:177], s[0:1], 0, v[176:177]
	global_load_lds_dwordx4 v[174:175], off
	v_subrev_u32_e32 v248, s6, v174
	v_add_u32_e32 v174, 0x8000, v179
	s_nop 0
	v_readfirstlane_b32 s17, v174
	s_mov_b32 m0, s17
	s_nop 0
	global_load_lds_dwordx4 v[176:177], off
	v_subrev_u32_e32 v247, s0, v176
	v_lshl_add_u64 v[176:177], s[0:1], 0, v[180:181]
	v_add_u32_e32 v180, 0xa000, v179
	s_nop 0
	v_readfirstlane_b32 s17, v180
	v_add_u32_e32 v180, 0xc000, v179
	s_mov_b32 m0, s17
	v_readfirstlane_b32 s17, v180
	v_add_u32_e32 v180, 0xe000, v179
	global_load_lds_dwordx4 v[176:177], off
	v_subrev_u32_e32 v246, s0, v176
	v_lshl_add_u64 v[176:177], s[0:1], 0, v[184:185]
	s_mov_b32 m0, s17
	v_readfirstlane_b32 s17, v180
	global_load_lds_dwordx4 v[176:177], off
	v_subrev_u32_e32 v245, s0, v176
	v_lshl_add_u64 v[176:177], s[0:1], 0, v[182:183]
	s_mov_b32 m0, s17
	s_nop 0
	global_load_lds_dwordx4 v[176:177], off
	v_subrev_u32_e32 v244, s0, v176
	s_add_u32 s98, s6, 0x80
	s_addc_u32 s99, s7, 0
	s_add_u32 s100, s0, 0x80
	s_addc_u32 s101, s1, 0
	v_readfirstlane_b32 s26, v179
	s_bfe_u32 s26, s26, 0x1000a
	s_branch .Lg_rot314_main

; #define LDB_(dst, ks) _Pragma("unroll") for (int n = 0; n < 4; ++n) dst[n] = *(const bf16x8*)(sB + b_off + n * 2048 + (ks) * 1024)
; #define LDA_(dst, ks, h) _Pragma("unroll") for (int m = 0; m < 4; ++m) dst[m] = *(const bf16x8*)(sA + a_off + ((h) * 4 + m) * 2048 + (ks) * 1024)
; #define MMA_(A, B, h) _Pragma("unroll") for (int m = 0; m < 4; ++m) _Pragma("unroll") for (int n = 0; n < 4; ++n) \
;       acc[(h) * 4 + m][n] = SWAP ? MFMA16(B[n], A[m], acc[(h) * 4 + m][n]) : MFMA16(A[m], B[n], acc[(h) * 4 + m][n])
; template <int MF, int NF, bool SWAP = true>
; DI void gemm_main(f32x4 (&acc)[MF][NF], const u16* __restrict__ Ab, int lda, const u16* __restrict__ Bb, int ldb,
;                   int K, char* shm) {
;     ...
;     if constexpr (MF == 8 && NF == 4) {
;       bf16x8 B0[4], B1[4], A0[4], A1[4], A2[4], A3[4];
;     ...
;       LDB_(B0, 0); LDA_(A0, 0, 0);
;       LDA_(A1, 0, 1); MMA_(A0, B0, 0);
;       LDB_(B1, 1); LDA_(A2, 1, 0); MMA_(A1, B0, 1);
;       LDA_(A3, 1, 1); MMA_(A2, B1, 0);
;       MMA_(A3, B1, 1);
.Lg_rot314_main:
	s_waitcnt lgkmcnt(6)
	v_mfma_f32_16x16x32_bf16 v[124:127], v[138:141], v[142:145], v[124:127]
	s_waitcnt lgkmcnt(5)
	v_mfma_f32_16x16x32_bf16 v[120:123], v[138:141], v[146:149], v[120:123]
	s_waitcnt lgkmcnt(4)
	v_mfma_f32_16x16x32_bf16 v[116:119], v[138:141], v[150:153], v[116:119]
	s_waitcnt lgkmcnt(3)
	v_mfma_f32_16x16x32_bf16 v[112:115], v[138:141], v[154:157], v[112:115]
	ds_read_b128 v[138:141], v186 offset:10240
	v_mfma_f32_16x16x32_bf16 v[108:111], v[158:161], v[142:145], v[108:111]
	v_mfma_f32_16x16x32_bf16 v[104:107], v[158:161], v[146:149], v[104:107]
	v_mfma_f32_16x16x32_bf16 v[100:103], v[158:161], v[150:153], v[100:103]
	v_mfma_f32_16x16x32_bf16 v[96:99], v[158:161], v[154:157], v[96:99]
	ds_read_b128 v[158:161], v186 offset:12288
	s_waitcnt lgkmcnt(4)
	v_mfma_f32_16x16x32_bf16 v[92:95], v[162:165], v[142:145], v[92:95]
	v_mfma_f32_16x16x32_bf16 v[88:91], v[162:165], v[146:149], v[88:91]
	v_mfma_f32_16x16x32_bf16 v[84:87], v[162:165], v[150:153], v[84:87]
	v_mfma_f32_16x16x32_bf16 v[80:83], v[162:165], v[154:157], v[80:83]
	ds_read_b128 v[162:165], v186 offset:14336
	s_waitcnt lgkmcnt(4)
	v_mfma_f32_16x16x32_bf16 v[76:79], v[166:169], v[142:145], v[76:79]
	v_mfma_f32_16x16x32_bf16 v[72:75], v[166:169], v[146:149], v[72:75]
	v_mfma_f32_16x16x32_bf16 v[68:71], v[166:169], v[150:153], v[68:71]
	v_mfma_f32_16x16x32_bf16 v[64:67], v[166:169], v[154:157], v[64:67]
	s_waitcnt lgkmcnt(0)
	s_cmp_eq_u32 s26, 0
	s_cbranch_scc1 .Lg_rot314_mbar
	s_cmp_gt_u32 s15, 14
	s_cbranch_scc1 .Lg_rot314_mw0
	s_waitcnt vmcnt(8)
	s_branch .Lg_rot314_mbar

; #define LDB_(dst, ks) _Pragma("unroll") for (int n = 0; n < 4; ++n) dst[n] = *(const bf16x8*)(sB + b_off + n * 2048 + (ks) * 1024)
; #define LDA_(dst, ks, h) _Pragma("unroll") for (int m = 0; m < 4; ++m) dst[m] = *(const bf16x8*)(sA + a_off + ((h) * 4 + m) * 2048 + (ks) * 1024)
; #define MMA_(A, B, h) _Pragma("unroll") for (int m = 0; m < 4; ++m) _Pragma("unroll") for (int n = 0; n < 4; ++n) \
;       acc[(h) * 4 + m][n] = SWAP ? MFMA16(B[n], A[m], acc[(h) * 4 + m][n]) : MFMA16(A[m], B[n], acc[(h) * 4 + m][n])
; template <int MF, int NF, bool SWAP = true>
; DI void gemm_main(f32x4 (&acc)[MF][NF], const u16* __restrict__ Ab, int lda, const u16* __restrict__ Bb, int ldb,
;                   int K, char* shm) {
;     ...
;   for (int t = 0; t < nt; ++t) {
;     const int cur = RING3 ? cur3 : (t & 1);
;     if constexpr (RING3) {
;       if (t + 2 < nt) G_STAGE(nxt3, t + 2);
;     } else {
;       if (t + 1 < nt) G_STAGE(cur ^ 1, t + 1);
;     }
;     const char* sA = shm + cur * STAGE;
;     const char* sB = sA + TILE_A;
;     if constexpr (MF == 8 && NF == 4) {
;       bf16x8 B0[4], B1[4], A0[4], A1[4], A2[4], A3[4];
;     ...
;       LDB_(B0, 0); LDA_(A0, 0, 0);
;       LDA_(A1, 0, 1); MMA_(A0, B0, 0);
;       LDB_(B1, 1); LDA_(A2, 1, 0); MMA_(A1, B0, 1);
;       LDA_(A3, 1, 1); MMA_(A2, B1, 0);
;       MMA_(A3, B1, 1);
.Lg_rot314_mbar:
	s_barrier
	s_cmp_lg_u32 s26, 0
	s_cbranch_scc1 .Lg_rot314_bplain
	s_cmp_gt_u32 s15, 13
	s_cbranch_scc1 .Lg_rot314_bplain
	ds_read_b128 v[192:195], v178 offset:33792
	v_mfma_f32_16x16x32_bf16 v[60:63], v[170:173], v[142:145], v[60:63]
	v_add_u32_e32 v255, s16, v128
	s_nop 0
	v_readfirstlane_b32 s17, v255
	s_nop 1
	s_add_u32 m0, s17, 0x0
	v_mfma_f32_16x16x32_bf16 v[56:59], v[170:173], v[146:149], v[56:59]
	global_load_lds_dwordx4 v251, s[98:99]
	s_add_u32 m0, s17, 0x2000
	ds_read_b128 v[196:199], v178 offset:35840
	v_mfma_f32_16x16x32_bf16 v[52:55], v[170:173], v[150:153], v[52:55]
	global_load_lds_dwordx4 v250, s[98:99]
	s_add_u32 m0, s17, 0x4000
	v_mfma_f32_16x16x32_bf16 v[48:51], v[170:173], v[154:157], v[48:51]
	global_load_lds_dwordx4 v249, s[98:99]
	s_add_u32 m0, s17, 0x6000
	ds_read_b128 v[212:215], v178 offset:37888
	v_mfma_f32_16x16x32_bf16 v[44:47], v[138:141], v[142:145], v[44:47]
	global_load_lds_dwordx4 v248, s[98:99]
	s_add_u32 m0, s17, 0x8000
	v_mfma_f32_16x16x32_bf16 v[40:43], v[138:141], v[146:149], v[40:43]
	global_load_lds_dwordx4 v247, s[100:101]
	s_add_u32 m0, s17, 0xa000
	ds_read_b128 v[216:219], v178 offset:39936
	v_mfma_f32_16x16x32_bf16 v[36:39], v[138:141], v[150:153], v[36:39]
	global_load_lds_dwordx4 v246, s[100:101]
	s_add_u32 m0, s17, 0xc000
	v_mfma_f32_16x16x32_bf16 v[32:35], v[138:141], v[154:157], v[32:35]
	global_load_lds_dwordx4 v245, s[100:101]
	s_add_u32 m0, s17, 0xe000
	ds_read_b128 v[138:141], v186 offset:1024
	v_mfma_f32_16x16x32_bf16 v[28:31], v[158:161], v[142:145], v[28:31]
	global_load_lds_dwordx4 v244, s[100:101]
	v_mfma_f32_16x16x32_bf16 v[24:27], v[158:161], v[146:149], v[24:27]
	ds_read_b128 v[182:185], v186 offset:3072
	v_mfma_f32_16x16x32_bf16 v[20:23], v[158:161], v[150:153], v[20:23]
	v_mfma_f32_16x16x32_bf16 v[16:19], v[158:161], v[154:157], v[16:19]
	ds_read_b128 v[158:161], v186 offset:5120
	v_mfma_f32_16x16x32_bf16 v[12:15], v[162:165], v[142:145], v[12:15]
	v_mfma_f32_16x16x32_bf16 v[4:7], v[162:165], v[146:149], v[4:7]
	ds_read_b128 v[142:145], v186 offset:7168
	v_mfma_f32_16x16x32_bf16 v[0:3], v[162:165], v[150:153], v[0:3]
	v_mfma_f32_16x16x32_bf16 v[8:11], v[162:165], v[154:157], v[8:11]
	ds_read_b128 v[188:191], v186 offset:9216
	s_waitcnt lgkmcnt(4)
	v_mfma_f32_16x16x32_bf16 v[124:127], v[138:141], v[192:195], v[124:127]
	v_mfma_f32_16x16x32_bf16 v[120:123], v[138:141], v[196:199], v[120:123]
	v_mfma_f32_16x16x32_bf16 v[116:119], v[138:141], v[212:215], v[116:119]
	v_mfma_f32_16x16x32_bf16 v[112:115], v[138:141], v[216:219], v[112:115]
	ds_read_b128 v[220:223], v186 offset:11264
	s_waitcnt lgkmcnt(4)
	v_mfma_f32_16x16x32_bf16 v[108:111], v[182:185], v[192:195], v[108:111]
	v_mfma_f32_16x16x32_bf16 v[104:107], v[182:185], v[196:199], v[104:107]
	v_mfma_f32_16x16x32_bf16 v[100:103], v[182:185], v[212:215], v[100:103]
	v_mfma_f32_16x16x32_bf16 v[96:99], v[182:185], v[216:219], v[96:99]
	ds_read_b128 v[224:227], v186 offset:13312
	s_waitcnt lgkmcnt(4)
	v_mfma_f32_16x16x32_bf16 v[92:95], v[158:161], v[192:195], v[92:95]
	v_mfma_f32_16x16x32_bf16 v[88:91], v[158:161], v[196:199], v[88:91]
	v_mfma_f32_16x16x32_bf16 v[84:87], v[158:161], v[212:215], v[84:87]
	v_mfma_f32_16x16x32_bf16 v[80:83], v[158:161], v[216:219], v[80:83]
	ds_read_b128 v[228:231], v186 offset:15360
	s_waitcnt lgkmcnt(4)
	v_mfma_f32_16x16x32_bf16 v[76:79], v[142:145], v[192:195], v[76:79]
	v_mfma_f32_16x16x32_bf16 v[72:75], v[142:145], v[196:199], v[72:75]
	v_mfma_f32_16x16x32_bf16 v[68:71], v[142:145], v[212:215], v[68:71]
	v_mfma_f32_16x16x32_bf16 v[64:67], v[142:145], v[216:219], v[64:67]
	s_waitcnt lgkmcnt(0)
	s_waitcnt vmcnt(8)
	s_branch .Lg_rot314_ectl
; #define LDB_(dst, ks) _Pragma("unroll") for (int n = 0; n < 4; ++n) dst[n] = *(const bf16x8*)(sB + b_off + n * 2048 + (ks) * 1024)
; #define LDA_(dst, ks, h) _Pragma("unroll") for (int m = 0; m < 4; ++m) dst[m] = *(const bf16x8*)(sA + a_off + ((h) * 4 + m) * 2048 + (ks) * 1024)
; #define MMA_(A, B, h) _Pragma("unroll") for (int m = 0; m < 4; ++m) _Pragma("unroll") for (int n = 0; n < 4; ++n) \
;       acc[(h) * 4 + m][n] = SWAP ? MFMA16(B[n], A[m], acc[(h) * 4 + m][n]) : MFMA16(A[m], B[n], acc[(h) * 4 + m][n])
; template <int MF, int NF, bool SWAP = true>
; DI void gemm_main(f32x4 (&acc)[MF][NF], const u16* __restrict__ Ab, int lda, const u16* __restrict__ Bb, int ldb,
;                   int K, char* shm) {
;     ...
;       LDB_(B0, 0); LDA_(A0, 0, 0);
;       LDA_(A1, 0, 1); MMA_(A0, B0, 0);
;       LDB_(B1, 1); LDA_(A2, 1, 0); MMA_(A1, B0, 1);
;       LDA_(A3, 1, 1); MMA_(A2, B1, 0);
;       MMA_(A3, B1, 1);
;     ...
;     if constexpr (RING3) {
;       if (t + 2 < nt) asm volatile("s_waitcnt vmcnt(6)" ::: "memory");
;       else asm volatile("s_waitcnt vmcnt(0)" ::: "memory");
;       asm volatile("s_waitcnt lgkmcnt(0)" ::: "memory");
;       __builtin_amdgcn_s_barrier();
;       cur3 = (cur3 == 2) ? 0 : cur3 + 1;
;       nxt3 = (nxt3 == 2) ? 0 : nxt3 + 1;
;     } else {
;       asm volatile("s_waitcnt vmcnt(0)" ::: "memory");
;       __syncthreads();
;     }
.Lg_rot314_bplain:
	ds_read_b128 v[192:195], v178 offset:33792
	v_mfma_f32_16x16x32_bf16 v[60:63], v[170:173], v[142:145], v[60:63]
	v_mfma_f32_16x16x32_bf16 v[56:59], v[170:173], v[146:149], v[56:59]
	ds_read_b128 v[196:199], v178 offset:35840
	v_mfma_f32_16x16x32_bf16 v[52:55], v[170:173], v[150:153], v[52:55]
	v_mfma_f32_16x16x32_bf16 v[48:51], v[170:173], v[154:157], v[48:51]
	ds_read_b128 v[212:215], v178 offset:37888
	v_mfma_f32_16x16x32_bf16 v[44:47], v[138:141], v[142:145], v[44:47]
	v_mfma_f32_16x16x32_bf16 v[40:43], v[138:141], v[146:149], v[40:43]
	ds_read_b128 v[216:219], v178 offset:39936
	v_mfma_f32_16x16x32_bf16 v[36:39], v[138:141], v[150:153], v[36:39]
	v_mfma_f32_16x16x32_bf16 v[32:35], v[138:141], v[154:157], v[32:35]
	ds_read_b128 v[138:141], v186 offset:1024
	v_mfma_f32_16x16x32_bf16 v[28:31], v[158:161], v[142:145], v[28:31]
	v_mfma_f32_16x16x32_bf16 v[24:27], v[158:161], v[146:149], v[24:27]
	ds_read_b128 v[182:185], v186 offset:3072
	v_mfma_f32_16x16x32_bf16 v[20:23], v[158:161], v[150:153], v[20:23]
	v_mfma_f32_16x16x32_bf16 v[16:19], v[158:161], v[154:157], v[16:19]
	ds_read_b128 v[158:161], v186 offset:5120
	v_mfma_f32_16x16x32_bf16 v[12:15], v[162:165], v[142:145], v[12:15]
	v_mfma_f32_16x16x32_bf16 v[4:7], v[162:165], v[146:149], v[4:7]
	ds_read_b128 v[142:145], v186 offset:7168
	v_mfma_f32_16x16x32_bf16 v[0:3], v[162:165], v[150:153], v[0:3]
	v_mfma_f32_16x16x32_bf16 v[8:11], v[162:165], v[154:157], v[8:11]
	ds_read_b128 v[188:191], v186 offset:9216
	s_waitcnt lgkmcnt(4)
	v_mfma_f32_16x16x32_bf16 v[124:127], v[138:141], v[192:195], v[124:127]
	v_mfma_f32_16x16x32_bf16 v[120:123], v[138:141], v[196:199], v[120:123]
	v_mfma_f32_16x16x32_bf16 v[116:119], v[138:141], v[212:215], v[116:119]
	v_mfma_f32_16x16x32_bf16 v[112:115], v[138:141], v[216:219], v[112:115]
	ds_read_b128 v[220:223], v186 offset:11264
	s_waitcnt lgkmcnt(4)
	v_mfma_f32_16x16x32_bf16 v[108:111], v[182:185], v[192:195], v[108:111]
	v_mfma_f32_16x16x32_bf16 v[104:107], v[182:185], v[196:199], v[104:107]
	v_mfma_f32_16x16x32_bf16 v[100:103], v[182:185], v[212:215], v[100:103]
	v_mfma_f32_16x16x32_bf16 v[96:99], v[182:185], v[216:219], v[96:99]
	ds_read_b128 v[224:227], v186 offset:13312
	s_waitcnt lgkmcnt(4)
	v_mfma_f32_16x16x32_bf16 v[92:95], v[158:161], v[192:195], v[92:95]
	v_mfma_f32_16x16x32_bf16 v[88:91], v[158:161], v[196:199], v[88:91]
	v_mfma_f32_16x16x32_bf16 v[84:87], v[158:161], v[212:215], v[84:87]
	v_mfma_f32_16x16x32_bf16 v[80:83], v[158:161], v[216:219], v[80:83]
	ds_read_b128 v[228:231], v186 offset:15360
	s_waitcnt lgkmcnt(4)
	v_mfma_f32_16x16x32_bf16 v[76:79], v[142:145], v[192:195], v[76:79]
	v_mfma_f32_16x16x32_bf16 v[72:75], v[142:145], v[196:199], v[72:75]
	v_mfma_f32_16x16x32_bf16 v[68:71], v[142:145], v[212:215], v[68:71]
	v_mfma_f32_16x16x32_bf16 v[64:67], v[142:145], v[216:219], v[64:67]
	s_waitcnt lgkmcnt(0)
	s_cmp_lg_u32 s26, 0
	s_cbranch_scc1 .Lg_rot314_ectl
	s_waitcnt vmcnt(0)
.Lg_rot314_ectl:
	s_add_i32 s13, s13, 64
	s_add_i32 s5, s5, 0x10000
	s_add_i32 s15, s15, 1
	s_cmpk_lg_i32 s13, 0x400
	s_barrier
	s_cbranch_scc1 .LBB0_314
	v_mfma_f32_16x16x32_bf16 v[60:63], v[188:191], v[192:195], v[60:63]
	v_mfma_f32_16x16x32_bf16 v[56:59], v[188:191], v[196:199], v[56:59]
	v_mfma_f32_16x16x32_bf16 v[52:55], v[188:191], v[212:215], v[52:55]
	v_mfma_f32_16x16x32_bf16 v[48:51], v[188:191], v[216:219], v[48:51]
	v_mfma_f32_16x16x32_bf16 v[44:47], v[220:223], v[192:195], v[44:47]
	v_mfma_f32_16x16x32_bf16 v[40:43], v[220:223], v[196:199], v[40:43]
	v_mfma_f32_16x16x32_bf16 v[36:39], v[220:223], v[212:215], v[36:39]
	v_mfma_f32_16x16x32_bf16 v[32:35], v[220:223], v[216:219], v[32:35]
	v_mfma_f32_16x16x32_bf16 v[28:31], v[224:227], v[192:195], v[28:31]
	v_mfma_f32_16x16x32_bf16 v[24:27], v[224:227], v[196:199], v[24:27]
	v_mfma_f32_16x16x32_bf16 v[20:23], v[224:227], v[212:215], v[20:23]
	v_mfma_f32_16x16x32_bf16 v[16:19], v[224:227], v[216:219], v[16:19]
	v_mfma_f32_16x16x32_bf16 v[12:15], v[228:231], v[192:195], v[12:15]
	v_mfma_f32_16x16x32_bf16 v[4:7], v[228:231], v[196:199], v[4:7]
	v_mfma_f32_16x16x32_bf16 v[0:3], v[228:231], v[212:215], v[0:3]
	v_mfma_f32_16x16x32_bf16 v[8:11], v[228:231], v[216:219], v[8:11]
	s_nop 7
	s_nop 1

; #define LDB_(dst, ks) _Pragma("unroll") for (int n = 0; n < 4; ++n) dst[n] = *(const bf16x8*)(sB + b_off + n * 2048 + (ks) * 1024)
; #define LDA_(dst, ks, h) _Pragma("unroll") for (int m = 0; m < 4; ++m) dst[m] = *(const bf16x8*)(sA + a_off + ((h) * 4 + m) * 2048 + (ks) * 1024)
; #define MMA_(A, B, h) _Pragma("unroll") for (int m = 0; m < 4; ++m) _Pragma("unroll") for (int n = 0; n < 4; ++n) \
;       acc[(h) * 4 + m][n] = SWAP ? MFMA16(B[n], A[m], acc[(h) * 4 + m][n]) : MFMA16(A[m], B[n], acc[(h) * 4 + m][n])
; template <int MF, int NF, bool SWAP = true>
; DI void gemm_main(f32x4 (&acc)[MF][NF], const u16* __restrict__ Ab, int lda, const u16* __restrict__ Bb, int ldb,
;                   int K, char* shm) {
;     ...
;   for (int t = 0; t < nt; ++t) {
;     const int cur = RING3 ? cur3 : (t & 1);
;     if constexpr (RING3) {
;       if (t + 2 < nt) G_STAGE(nxt3, t + 2);
;     } else {
;       if (t + 1 < nt) G_STAGE(cur ^ 1, t + 1);
;     }
;     const char* sA = shm + cur * STAGE;
;     const char* sB = sA + TILE_A;
;     if constexpr (MF == 8 && NF == 4) {
;       bf16x8 B0[4], B1[4], A0[4], A1[4], A2[4], A3[4];
;     ...
;       LDB_(B0, 0); LDA_(A0, 0, 0);
;       LDA_(A1, 0, 1); MMA_(A0, B0, 0);
;       LDB_(B1, 1); LDA_(A2, 1, 0); MMA_(A1, B0, 1);
;       LDA_(A3, 1, 1); MMA_(A2, B1, 0);
;       MMA_(A3, B1, 1);
.LBB0_553:
	s_and_b32 s21, s18, 0x10000
	v_add_u32_e32 v162, s21, v143
	v_add_u32_e32 v186, v162, v142
	ds_read_b128 v[146:149], v186 offset:32768
	ds_read_b128 v[150:153], v186 offset:34816
	ds_read_b128 v[154:157], v186 offset:36864
	ds_read_b128 v[158:161], v186 offset:38912
	v_add_u32_e32 v194, v162, v141
	ds_read_b128 v[162:165], v194
	ds_read_b128 v[166:169], v194 offset:2048
	ds_read_b128 v[170:173], v194 offset:4096
	ds_read_b128 v[174:177], v194 offset:6144
	ds_read_b128 v[178:181], v194 offset:8192
	s_cmp_gt_u32 s20, 2
	s_cbranch_scc1 .Lg_rot553_last
	s_cmp_eq_u32 s20, 0
	s_cbranch_scc1 .Lg_rot553_first
	s_cmp_lg_u32 s26, 0
	s_cbranch_scc0 .Lg_rot553_ehead
	v_mfma_f32_16x16x32_bf16 v[60:63], v[196:199], v[212:215], v[60:63]
	s_xor_b32 s22, s21, 0x10000
	v_add_u32_e32 v195, s22, v132
	v_mfma_f32_16x16x32_bf16 v[56:59], v[216:219], v[212:215], v[56:59]
	s_nop 0
	v_readfirstlane_b32 s22, v195
	s_nop 1
	s_add_u32 m0, s22, 0x0
	v_mfma_f32_16x16x32_bf16 v[52:55], v[220:223], v[212:215], v[52:55]
	global_load_lds_dwordx4 v251, s[98:99]
	s_add_u32 m0, s22, 0x2000
	v_mfma_f32_16x16x32_bf16 v[48:51], v[224:227], v[212:215], v[48:51]
	global_load_lds_dwordx4 v250, s[98:99]
	s_add_u32 m0, s22, 0x4000
	v_mfma_f32_16x16x32_bf16 v[44:47], v[196:199], v[228:231], v[44:47]
	global_load_lds_dwordx4 v249, s[98:99]
	s_add_u32 m0, s22, 0x6000
	v_mfma_f32_16x16x32_bf16 v[40:43], v[216:219], v[228:231], v[40:43]
	global_load_lds_dwordx4 v248, s[98:99]
	s_add_u32 m0, s22, 0x8000
	v_mfma_f32_16x16x32_bf16 v[36:39], v[220:223], v[228:231], v[36:39]
	global_load_lds_dwordx4 v247, s[100:101]
	s_add_u32 m0, s22, 0xa000
	v_mfma_f32_16x16x32_bf16 v[32:35], v[224:227], v[228:231], v[32:35]
	global_load_lds_dwordx4 v246, s[100:101]
	s_add_u32 m0, s22, 0xc000
	v_mfma_f32_16x16x32_bf16 v[28:31], v[196:199], v[232:235], v[28:31]
	global_load_lds_dwordx4 v245, s[100:101]
	s_add_u32 m0, s22, 0xe000
	v_mfma_f32_16x16x32_bf16 v[24:27], v[216:219], v[232:235], v[24:27]
	global_load_lds_dwordx4 v244, s[100:101]
	v_mfma_f32_16x16x32_bf16 v[20:23], v[220:223], v[232:235], v[20:23]
	s_add_u32 s98, s98, 0x80
	s_addc_u32 s99, s99, 0
	s_add_u32 s100, s100, 0x80
	s_addc_u32 s101, s101, 0
	v_mfma_f32_16x16x32_bf16 v[16:19], v[224:227], v[232:235], v[16:19]
	v_mfma_f32_16x16x32_bf16 v[12:15], v[196:199], v[236:239], v[12:15]
	v_mfma_f32_16x16x32_bf16 v[4:7], v[216:219], v[236:239], v[4:7]
	v_mfma_f32_16x16x32_bf16 v[0:3], v[220:223], v[236:239], v[0:3]
	v_mfma_f32_16x16x32_bf16 v[8:11], v[224:227], v[236:239], v[8:11]
	s_branch .Lg_rot553_main
.Lg_rot553_ehead:
	v_mfma_f32_16x16x32_bf16 v[60:63], v[196:199], v[212:215], v[60:63]
	s_add_u32 s98, s98, 0x80
	s_addc_u32 s99, s99, 0
	s_add_u32 s100, s100, 0x80
	s_addc_u32 s101, s101, 0
	v_mfma_f32_16x16x32_bf16 v[56:59], v[216:219], v[212:215], v[56:59]
	v_mfma_f32_16x16x32_bf16 v[52:55], v[220:223], v[212:215], v[52:55]
	v_mfma_f32_16x16x32_bf16 v[48:51], v[224:227], v[212:215], v[48:51]
	v_mfma_f32_16x16x32_bf16 v[44:47], v[196:199], v[228:231], v[44:47]
	v_mfma_f32_16x16x32_bf16 v[40:43], v[216:219], v[228:231], v[40:43]
	v_mfma_f32_16x16x32_bf16 v[36:39], v[220:223], v[228:231], v[36:39]
	v_mfma_f32_16x16x32_bf16 v[32:35], v[224:227], v[228:231], v[32:35]
	v_mfma_f32_16x16x32_bf16 v[28:31], v[196:199], v[232:235], v[28:31]
	v_mfma_f32_16x16x32_bf16 v[24:27], v[216:219], v[232:235], v[24:27]
	v_mfma_f32_16x16x32_bf16 v[20:23], v[220:223], v[232:235], v[20:23]
	v_mfma_f32_16x16x32_bf16 v[16:19], v[224:227], v[232:235], v[16:19]
	v_mfma_f32_16x16x32_bf16 v[12:15], v[196:199], v[236:239], v[12:15]
	v_mfma_f32_16x16x32_bf16 v[4:7], v[216:219], v[236:239], v[4:7]
	v_mfma_f32_16x16x32_bf16 v[0:3], v[220:223], v[236:239], v[0:3]
	v_mfma_f32_16x16x32_bf16 v[8:11], v[224:227], v[236:239], v[8:11]
	s_branch .Lg_rot553_main
.Lg_rot553_first:
	s_xor_b32 s22, s21, 0x10000
	v_add_u32_e32 v187, s19, v145
	v_add_u32_e32 v195, s22, v132
	v_add_u32_e32 v182, 64, v187
	v_ashrrev_i32_e32 v183, 31, v182
	v_readfirstlane_b32 s22, v195
	v_lshl_add_u64 v[182:183], v[182:183], 1, s[4:5]
	s_mov_b32 m0, s22
	v_add_u32_e32 v211, 0x2000, v195
	global_load_lds_dwordx4 v[182:183], off
	v_subrev_u32_e32 v251, s4, v182
	v_add_u32_e32 v182, 0x7040, v187
	v_ashrrev_i32_e32 v183, 31, v182
	v_readfirstlane_b32 s22, v211
	v_lshl_add_u64 v[182:183], v[182:183], 1, s[4:5]
	s_mov_b32 m0, s22
	v_add_u32_e32 v211, 0x4000, v195
	global_load_lds_dwordx4 v[182:183], off
	v_subrev_u32_e32 v250, s4, v182
	v_add_u32_e32 v182, 0xe040, v187
	v_ashrrev_i32_e32 v183, 31, v182
	v_readfirstlane_b32 s22, v211
	v_lshl_add_u64 v[182:183], v[182:183], 1, s[4:5]
	s_mov_b32 m0, s22
	v_add_u32_e32 v211, s19, v144
	global_load_lds_dwordx4 v[182:183], off
	v_subrev_u32_e32 v249, s4, v182
	v_add_u32_e32 v182, 0x15040, v187
	v_add_u32_e32 v187, 0x6000, v195
	v_ashrrev_i32_e32 v183, 31, v182
	v_readfirstlane_b32 s22, v187
	v_lshl_add_u64 v[182:183], v[182:183], 1, s[4:5]
	s_mov_b32 m0, s22
	v_add_u32_e32 v187, 0x8000, v195
	global_load_lds_dwordx4 v[182:183], off
	v_subrev_u32_e32 v248, s4, v182
	v_add_u32_e32 v182, 64, v211
	v_ashrrev_i32_e32 v183, 31, v182
	v_readfirstlane_b32 s22, v187
	v_lshl_add_u64 v[182:183], v[182:183], 1, s[6:7]
	s_mov_b32 m0, s22
	v_add_u32_e32 v187, 0xa000, v195
	global_load_lds_dwordx4 v[182:183], off
	v_subrev_u32_e32 v247, s6, v182
	v_add_u32_e32 v182, 0x4040, v211
	v_ashrrev_i32_e32 v183, 31, v182
	v_readfirstlane_b32 s22, v187
	v_lshl_add_u64 v[182:183], v[182:183], 1, s[6:7]
	s_mov_b32 m0, s22
	v_add_u32_e32 v187, 0xc000, v195
	global_load_lds_dwordx4 v[182:183], off
	v_subrev_u32_e32 v246, s6, v182
	v_add_u32_e32 v182, 0x8040, v211
	v_ashrrev_i32_e32 v183, 31, v182
	v_readfirstlane_b32 s22, v187
	v_lshl_add_u64 v[182:183], v[182:183], 1, s[6:7]
	s_mov_b32 m0, s22
	v_add_u32_e32 v195, 0xe000, v195
	global_load_lds_dwordx4 v[182:183], off
	v_subrev_u32_e32 v245, s6, v182
	v_add_u32_e32 v182, 0xc040, v211
	v_ashrrev_i32_e32 v183, 31, v182
	v_readfirstlane_b32 s22, v195
	v_lshl_add_u64 v[182:183], v[182:183], 1, s[6:7]
	s_mov_b32 m0, s22
	s_nop 0
	global_load_lds_dwordx4 v[182:183], off
	v_subrev_u32_e32 v244, s6, v182
	s_add_u32 s98, s4, 0x80
	s_addc_u32 s99, s5, 0
	s_add_u32 s100, s6, 0x80
	s_addc_u32 s101, s7, 0
	v_readfirstlane_b32 s26, v195
	s_bfe_u32 s26, s26, 0x1000a
	s_branch .Lg_rot553_main

; #define LDB_(dst, ks) _Pragma("unroll") for (int n = 0; n < 4; ++n) dst[n] = *(const bf16x8*)(sB + b_off + n * 2048 + (ks) * 1024)
; #define LDA_(dst, ks, h) _Pragma("unroll") for (int m = 0; m < 4; ++m) dst[m] = *(const bf16x8*)(sA + a_off + ((h) * 4 + m) * 2048 + (ks) * 1024)
; #define MMA_(A, B, h) _Pragma("unroll") for (int m = 0; m < 4; ++m) _Pragma("unroll") for (int n = 0; n < 4; ++n) \
;       acc[(h) * 4 + m][n] = SWAP ? MFMA16(B[n], A[m], acc[(h) * 4 + m][n]) : MFMA16(A[m], B[n], acc[(h) * 4 + m][n])
; template <int MF, int NF, bool SWAP = true>
; DI void gemm_main(f32x4 (&acc)[MF][NF], const u16* __restrict__ Ab, int lda, const u16* __restrict__ Bb, int ldb,
;                   int K, char* shm) {
;     ...
;       LDB_(B0, 0); LDA_(A0, 0, 0);
;       LDA_(A1, 0, 1); MMA_(A0, B0, 0);
;       LDB_(B1, 1); LDA_(A2, 1, 0); MMA_(A1, B0, 1);
.Lg_rot553_main:
	s_waitcnt lgkmcnt(4)
	v_mfma_f32_16x16x32_bf16 v[124:127], v[146:149], v[162:165], v[124:127]
	v_mfma_f32_16x16x32_bf16 v[120:123], v[150:153], v[162:165], v[120:123]
	v_mfma_f32_16x16x32_bf16 v[116:119], v[154:157], v[162:165], v[116:119]
	v_mfma_f32_16x16x32_bf16 v[112:115], v[158:161], v[162:165], v[112:115]
	ds_read_b128 v[162:165], v194 offset:10240
	s_waitcnt lgkmcnt(4)
	v_mfma_f32_16x16x32_bf16 v[108:111], v[146:149], v[166:169], v[108:111]
	v_mfma_f32_16x16x32_bf16 v[104:107], v[150:153], v[166:169], v[104:107]
	v_mfma_f32_16x16x32_bf16 v[100:103], v[154:157], v[166:169], v[100:103]
	v_mfma_f32_16x16x32_bf16 v[96:99], v[158:161], v[166:169], v[96:99]
	ds_read_b128 v[166:169], v194 offset:12288
	s_waitcnt lgkmcnt(4)
	v_mfma_f32_16x16x32_bf16 v[92:95], v[146:149], v[170:173], v[92:95]
	v_mfma_f32_16x16x32_bf16 v[88:91], v[150:153], v[170:173], v[88:91]
	v_mfma_f32_16x16x32_bf16 v[84:87], v[154:157], v[170:173], v[84:87]
	v_mfma_f32_16x16x32_bf16 v[80:83], v[158:161], v[170:173], v[80:83]
	ds_read_b128 v[170:173], v194 offset:14336
	s_waitcnt lgkmcnt(4)
	v_mfma_f32_16x16x32_bf16 v[76:79], v[146:149], v[174:177], v[76:79]
	v_mfma_f32_16x16x32_bf16 v[72:75], v[150:153], v[174:177], v[72:75]
	v_mfma_f32_16x16x32_bf16 v[68:71], v[154:157], v[174:177], v[68:71]
	v_mfma_f32_16x16x32_bf16 v[64:67], v[158:161], v[174:177], v[64:67]
	s_waitcnt lgkmcnt(0)
	s_cmp_eq_u32 s26, 0
	s_cbranch_scc1 .Lg_rot553_mbar
	s_cmp_gt_u32 s20, 2
	s_cbranch_scc1 .Lg_rot553_mw0
	s_waitcnt vmcnt(8)
	s_branch .Lg_rot553_mbar

; #define LDB_(dst, ks) _Pragma("unroll") for (int n = 0; n < 4; ++n) dst[n] = *(const bf16x8*)(sB + b_off + n * 2048 + (ks) * 1024)
; #define LDA_(dst, ks, h) _Pragma("unroll") for (int m = 0; m < 4; ++m) dst[m] = *(const bf16x8*)(sA + a_off + ((h) * 4 + m) * 2048 + (ks) * 1024)
; #define MMA_(A, B, h) _Pragma("unroll") for (int m = 0; m < 4; ++m) _Pragma("unroll") for (int n = 0; n < 4; ++n) \
;       acc[(h) * 4 + m][n] = SWAP ? MFMA16(B[n], A[m], acc[(h) * 4 + m][n]) : MFMA16(A[m], B[n], acc[(h) * 4 + m][n])
; template <int MF, int NF, bool SWAP = true>
; DI void gemm_main(f32x4 (&acc)[MF][NF], const u16* __restrict__ Ab, int lda, const u16* __restrict__ Bb, int ldb,
;                   int K, char* shm) {
;     ...
;       LDB_(B1, 1); LDA_(A2, 1, 0); MMA_(A1, B0, 1);
;       LDA_(A3, 1, 1); MMA_(A2, B1, 0);
;       MMA_(A3, B1, 1);
.Lg_rot553_mbar:
	s_barrier
	s_cmp_lg_u32 s26, 0
	s_cbranch_scc1 .Lg_rot553_bplain
	s_cmp_gt_u32 s20, 1
	s_cbranch_scc1 .Lg_rot553_bplain
	ds_read_b128 v[196:199], v186 offset:33792
	v_mfma_f32_16x16x32_bf16 v[60:63], v[146:149], v[178:181], v[60:63]
	v_add_u32_e32 v255, s21, v132
	s_nop 0
	v_readfirstlane_b32 s22, v255
	s_nop 1
	s_add_u32 m0, s22, 0x0
	v_mfma_f32_16x16x32_bf16 v[56:59], v[150:153], v[178:181], v[56:59]
	global_load_lds_dwordx4 v251, s[98:99]
	s_add_u32 m0, s22, 0x2000
	ds_read_b128 v[216:219], v186 offset:35840
	v_mfma_f32_16x16x32_bf16 v[52:55], v[154:157], v[178:181], v[52:55]
	global_load_lds_dwordx4 v250, s[98:99]
	s_add_u32 m0, s22, 0x4000
	v_mfma_f32_16x16x32_bf16 v[48:51], v[158:161], v[178:181], v[48:51]
	global_load_lds_dwordx4 v249, s[98:99]
	s_add_u32 m0, s22, 0x6000
	ds_read_b128 v[220:223], v186 offset:37888
	v_mfma_f32_16x16x32_bf16 v[44:47], v[146:149], v[162:165], v[44:47]
	global_load_lds_dwordx4 v248, s[98:99]
	s_add_u32 m0, s22, 0x8000
	v_mfma_f32_16x16x32_bf16 v[40:43], v[150:153], v[162:165], v[40:43]
	global_load_lds_dwordx4 v247, s[100:101]
	s_add_u32 m0, s22, 0xa000
	ds_read_b128 v[224:227], v186 offset:39936
	v_mfma_f32_16x16x32_bf16 v[36:39], v[154:157], v[162:165], v[36:39]
	global_load_lds_dwordx4 v246, s[100:101]
	s_add_u32 m0, s22, 0xc000
	v_mfma_f32_16x16x32_bf16 v[32:35], v[158:161], v[162:165], v[32:35]
	global_load_lds_dwordx4 v245, s[100:101]
	s_add_u32 m0, s22, 0xe000
	ds_read_b128 v[162:165], v194 offset:1024
	v_mfma_f32_16x16x32_bf16 v[28:31], v[146:149], v[166:169], v[28:31]
	global_load_lds_dwordx4 v244, s[100:101]
	v_mfma_f32_16x16x32_bf16 v[24:27], v[150:153], v[166:169], v[24:27]
	ds_read_b128 v[190:193], v194 offset:3072
	v_mfma_f32_16x16x32_bf16 v[20:23], v[154:157], v[166:169], v[20:23]
	v_mfma_f32_16x16x32_bf16 v[16:19], v[158:161], v[166:169], v[16:19]
	ds_read_b128 v[166:169], v194 offset:5120
	v_mfma_f32_16x16x32_bf16 v[12:15], v[146:149], v[170:173], v[12:15]
	v_mfma_f32_16x16x32_bf16 v[4:7], v[150:153], v[170:173], v[4:7]
	ds_read_b128 v[146:149], v194 offset:7168
	v_mfma_f32_16x16x32_bf16 v[0:3], v[154:157], v[170:173], v[0:3]
	v_mfma_f32_16x16x32_bf16 v[8:11], v[158:161], v[170:173], v[8:11]
	ds_read_b128 v[212:215], v194 offset:9216
	s_waitcnt lgkmcnt(4)
	v_mfma_f32_16x16x32_bf16 v[124:127], v[196:199], v[162:165], v[124:127]
	v_mfma_f32_16x16x32_bf16 v[120:123], v[216:219], v[162:165], v[120:123]
	v_mfma_f32_16x16x32_bf16 v[116:119], v[220:223], v[162:165], v[116:119]
	v_mfma_f32_16x16x32_bf16 v[112:115], v[224:227], v[162:165], v[112:115]
	ds_read_b128 v[228:231], v194 offset:11264
	s_waitcnt lgkmcnt(4)
	v_mfma_f32_16x16x32_bf16 v[108:111], v[196:199], v[190:193], v[108:111]
	v_mfma_f32_16x16x32_bf16 v[104:107], v[216:219], v[190:193], v[104:107]
	v_mfma_f32_16x16x32_bf16 v[100:103], v[220:223], v[190:193], v[100:103]
	v_mfma_f32_16x16x32_bf16 v[96:99], v[224:227], v[190:193], v[96:99]
	ds_read_b128 v[232:235], v194 offset:13312
	s_waitcnt lgkmcnt(4)
	v_mfma_f32_16x16x32_bf16 v[92:95], v[196:199], v[166:169], v[92:95]
	v_mfma_f32_16x16x32_bf16 v[88:91], v[216:219], v[166:169], v[88:91]
	v_mfma_f32_16x16x32_bf16 v[84:87], v[220:223], v[166:169], v[84:87]
	v_mfma_f32_16x16x32_bf16 v[80:83], v[224:227], v[166:169], v[80:83]
	ds_read_b128 v[236:239], v194 offset:15360
	s_waitcnt lgkmcnt(4)
	v_mfma_f32_16x16x32_bf16 v[76:79], v[196:199], v[146:149], v[76:79]
	v_mfma_f32_16x16x32_bf16 v[72:75], v[216:219], v[146:149], v[72:75]
	v_mfma_f32_16x16x32_bf16 v[68:71], v[220:223], v[146:149], v[68:71]
	v_mfma_f32_16x16x32_bf16 v[64:67], v[224:227], v[146:149], v[64:67]
	s_waitcnt lgkmcnt(0)
	s_waitcnt vmcnt(8)
	s_branch .Lg_rot553_ectl
; #define LDB_(dst, ks) _Pragma("unroll") for (int n = 0; n < 4; ++n) dst[n] = *(const bf16x8*)(sB + b_off + n * 2048 + (ks) * 1024)
; #define LDA_(dst, ks, h) _Pragma("unroll") for (int m = 0; m < 4; ++m) dst[m] = *(const bf16x8*)(sA + a_off + ((h) * 4 + m) * 2048 + (ks) * 1024)
; #define MMA_(A, B, h) _Pragma("unroll") for (int m = 0; m < 4; ++m) _Pragma("unroll") for (int n = 0; n < 4; ++n) \
;       acc[(h) * 4 + m][n] = SWAP ? MFMA16(B[n], A[m], acc[(h) * 4 + m][n]) : MFMA16(A[m], B[n], acc[(h) * 4 + m][n])
; template <int MF, int NF, bool SWAP = true>
; DI void gemm_main(f32x4 (&acc)[MF][NF], const u16* __restrict__ Ab, int lda, const u16* __restrict__ Bb, int ldb,
;                   int K, char* shm) {
;     ...
;       LDB_(B1, 1); LDA_(A2, 1, 0); MMA_(A1, B0, 1);
;       LDA_(A3, 1, 1); MMA_(A2, B1, 0);
;       MMA_(A3, B1, 1);
;     ...
;     if constexpr (RING3) {
;       if (t + 2 < nt) asm volatile("s_waitcnt vmcnt(6)" ::: "memory");
;       else asm volatile("s_waitcnt vmcnt(0)" ::: "memory");
;       asm volatile("s_waitcnt lgkmcnt(0)" ::: "memory");
;       __builtin_amdgcn_s_barrier();
;       cur3 = (cur3 == 2) ? 0 : cur3 + 1;
;       nxt3 = (nxt3 == 2) ? 0 : nxt3 + 1;
;     } else {
;       asm volatile("s_waitcnt vmcnt(0)" ::: "memory");
;       __syncthreads();
;     }
.Lg_rot553_bplain:
	ds_read_b128 v[196:199], v186 offset:33792
	v_mfma_f32_16x16x32_bf16 v[60:63], v[146:149], v[178:181], v[60:63]
	v_mfma_f32_16x16x32_bf16 v[56:59], v[150:153], v[178:181], v[56:59]
	ds_read_b128 v[216:219], v186 offset:35840
	v_mfma_f32_16x16x32_bf16 v[52:55], v[154:157], v[178:181], v[52:55]
	v_mfma_f32_16x16x32_bf16 v[48:51], v[158:161], v[178:181], v[48:51]
	ds_read_b128 v[220:223], v186 offset:37888
	v_mfma_f32_16x16x32_bf16 v[44:47], v[146:149], v[162:165], v[44:47]
	v_mfma_f32_16x16x32_bf16 v[40:43], v[150:153], v[162:165], v[40:43]
	ds_read_b128 v[224:227], v186 offset:39936
	v_mfma_f32_16x16x32_bf16 v[36:39], v[154:157], v[162:165], v[36:39]
	v_mfma_f32_16x16x32_bf16 v[32:35], v[158:161], v[162:165], v[32:35]
	ds_read_b128 v[162:165], v194 offset:1024
	v_mfma_f32_16x16x32_bf16 v[28:31], v[146:149], v[166:169], v[28:31]
	v_mfma_f32_16x16x32_bf16 v[24:27], v[150:153], v[166:169], v[24:27]
	ds_read_b128 v[190:193], v194 offset:3072
	v_mfma_f32_16x16x32_bf16 v[20:23], v[154:157], v[166:169], v[20:23]
	v_mfma_f32_16x16x32_bf16 v[16:19], v[158:161], v[166:169], v[16:19]
	ds_read_b128 v[166:169], v194 offset:5120
	v_mfma_f32_16x16x32_bf16 v[12:15], v[146:149], v[170:173], v[12:15]
	v_mfma_f32_16x16x32_bf16 v[4:7], v[150:153], v[170:173], v[4:7]
	ds_read_b128 v[146:149], v194 offset:7168
	v_mfma_f32_16x16x32_bf16 v[0:3], v[154:157], v[170:173], v[0:3]
	v_mfma_f32_16x16x32_bf16 v[8:11], v[158:161], v[170:173], v[8:11]
	ds_read_b128 v[212:215], v194 offset:9216
	s_waitcnt lgkmcnt(4)
	v_mfma_f32_16x16x32_bf16 v[124:127], v[196:199], v[162:165], v[124:127]
	v_mfma_f32_16x16x32_bf16 v[120:123], v[216:219], v[162:165], v[120:123]
	v_mfma_f32_16x16x32_bf16 v[116:119], v[220:223], v[162:165], v[116:119]
	v_mfma_f32_16x16x32_bf16 v[112:115], v[224:227], v[162:165], v[112:115]
	ds_read_b128 v[228:231], v194 offset:11264
	s_waitcnt lgkmcnt(4)
	v_mfma_f32_16x16x32_bf16 v[108:111], v[196:199], v[190:193], v[108:111]
	v_mfma_f32_16x16x32_bf16 v[104:107], v[216:219], v[190:193], v[104:107]
	v_mfma_f32_16x16x32_bf16 v[100:103], v[220:223], v[190:193], v[100:103]
	v_mfma_f32_16x16x32_bf16 v[96:99], v[224:227], v[190:193], v[96:99]
	ds_read_b128 v[232:235], v194 offset:13312
	s_waitcnt lgkmcnt(4)
	v_mfma_f32_16x16x32_bf16 v[92:95], v[196:199], v[166:169], v[92:95]
	v_mfma_f32_16x16x32_bf16 v[88:91], v[216:219], v[166:169], v[88:91]
	v_mfma_f32_16x16x32_bf16 v[84:87], v[220:223], v[166:169], v[84:87]
	v_mfma_f32_16x16x32_bf16 v[80:83], v[224:227], v[166:169], v[80:83]
	ds_read_b128 v[236:239], v194 offset:15360
	s_waitcnt lgkmcnt(4)
	v_mfma_f32_16x16x32_bf16 v[76:79], v[196:199], v[146:149], v[76:79]
	v_mfma_f32_16x16x32_bf16 v[72:75], v[216:219], v[146:149], v[72:75]
	v_mfma_f32_16x16x32_bf16 v[68:71], v[220:223], v[146:149], v[68:71]
	v_mfma_f32_16x16x32_bf16 v[64:67], v[224:227], v[146:149], v[64:67]
	s_waitcnt lgkmcnt(0)
	s_cmp_lg_u32 s26, 0
	s_cbranch_scc1 .Lg_rot553_ectl
	s_waitcnt vmcnt(0)
.Lg_rot553_ectl:
	s_add_i32 s19, s19, 64
	s_add_i32 s18, s18, 0x10000
	s_add_i32 s20, s20, 1
	s_cmpk_lg_i32 s19, 0x100
	s_barrier
	s_cbranch_scc1 .LBB0_553
	v_mfma_f32_16x16x32_bf16 v[60:63], v[196:199], v[212:215], v[60:63]
	v_mfma_f32_16x16x32_bf16 v[56:59], v[216:219], v[212:215], v[56:59]
	v_mfma_f32_16x16x32_bf16 v[52:55], v[220:223], v[212:215], v[52:55]
	v_mfma_f32_16x16x32_bf16 v[48:51], v[224:227], v[212:215], v[48:51]
	v_mfma_f32_16x16x32_bf16 v[44:47], v[196:199], v[228:231], v[44:47]
	v_mfma_f32_16x16x32_bf16 v[40:43], v[216:219], v[228:231], v[40:43]
	v_mfma_f32_16x16x32_bf16 v[36:39], v[220:223], v[228:231], v[36:39]
	v_mfma_f32_16x16x32_bf16 v[32:35], v[224:227], v[228:231], v[32:35]
	v_mfma_f32_16x16x32_bf16 v[28:31], v[196:199], v[232:235], v[28:31]
	v_mfma_f32_16x16x32_bf16 v[24:27], v[216:219], v[232:235], v[24:27]
	v_mfma_f32_16x16x32_bf16 v[20:23], v[220:223], v[232:235], v[20:23]
	v_mfma_f32_16x16x32_bf16 v[16:19], v[224:227], v[232:235], v[16:19]
	v_mfma_f32_16x16x32_bf16 v[12:15], v[196:199], v[236:239], v[12:15]
	v_mfma_f32_16x16x32_bf16 v[4:7], v[216:219], v[236:239], v[4:7]
	v_mfma_f32_16x16x32_bf16 v[0:3], v[220:223], v[236:239], v[0:3]
	v_mfma_f32_16x16x32_bf16 v[8:11], v[224:227], v[236:239], v[8:11]
	s_nop 7
	s_nop 1

; #define LDB_(dst, ks) _Pragma("unroll") for (int n = 0; n < 4; ++n) dst[n] = *(const bf16x8*)(sB + b_off + n * 2048 + (ks) * 1024)
; #define LDA_(dst, ks, h) _Pragma("unroll") for (int m = 0; m < 4; ++m) dst[m] = *(const bf16x8*)(sA + a_off + ((h) * 4 + m) * 2048 + (ks) * 1024)
; #define MMA_(A, B, h) _Pragma("unroll") for (int m = 0; m < 4; ++m) _Pragma("unroll") for (int n = 0; n < 4; ++n) \
;       acc[(h) * 4 + m][n] = SWAP ? MFMA16(B[n], A[m], acc[(h) * 4 + m][n]) : MFMA16(A[m], B[n], acc[(h) * 4 + m][n])
; template <int MF, int NF, bool SWAP = true>
; DI void gemm_main(f32x4 (&acc)[MF][NF], const u16* __restrict__ Ab, int lda, const u16* __restrict__ Bb, int ldb,
;                   int K, char* shm) {
;     ...
;   for (int t = 0; t < nt; ++t) {
;     const int cur = RING3 ? cur3 : (t & 1);
;     if constexpr (RING3) {
;       if (t + 2 < nt) G_STAGE(nxt3, t + 2);
;     } else {
;       if (t + 1 < nt) G_STAGE(cur ^ 1, t + 1);
;     }
;     const char* sA = shm + cur * STAGE;
;     const char* sB = sA + TILE_A;
;     if constexpr (MF == 8 && NF == 4) {
;       bf16x8 B0[4], B1[4], A0[4], A1[4], A2[4], A3[4];
;     ...
;       LDB_(B0, 0); LDA_(A0, 0, 0);
;       LDA_(A1, 0, 1); MMA_(A0, B0, 0);
;       LDB_(B1, 1); LDA_(A2, 1, 0); MMA_(A1, B0, 1);
;       LDA_(A3, 1, 1); MMA_(A2, B1, 0);
;       MMA_(A3, B1, 1);
.LBB0_589:
	s_and_b32 s21, s16, 0x10000
	v_add_u32_e32 v137, s21, v132
	v_add_u32_e32 v178, v137, v131
	ds_read_b128 v[138:141], v178 offset:32768
	ds_read_b128 v[142:145], v178 offset:34816
	ds_read_b128 v[146:149], v178 offset:36864
	ds_read_b128 v[150:153], v178 offset:38912
	v_add_u32_e32 v137, v137, v129
	ds_read_b128 v[154:157], v137
	ds_read_b128 v[158:161], v137 offset:2048
	ds_read_b128 v[162:165], v137 offset:4096
	ds_read_b128 v[166:169], v137 offset:6144
	ds_read_b128 v[170:173], v137 offset:8192
	s_cmp_gt_u32 s15, 14
	s_cbranch_scc1 .Lg_rot589_last
	s_cmp_eq_u32 s15, 0
	s_cbranch_scc1 .Lg_rot589_first
	s_cmp_lg_u32 s26, 0
	s_cbranch_scc0 .Lg_rot589_ehead
	v_mfma_f32_16x16x32_bf16 v[60:63], v[186:189], v[190:193], v[60:63]
	s_xor_b32 s22, s21, 0x10000
	v_add_u32_e32 v179, s22, v128
	v_mfma_f32_16x16x32_bf16 v[56:59], v[194:197], v[190:193], v[56:59]
	s_nop 0
	v_readfirstlane_b32 s22, v179
	s_nop 1
	s_add_u32 m0, s22, 0x0
	v_mfma_f32_16x16x32_bf16 v[52:55], v[198:201], v[190:193], v[52:55]
	global_load_lds_dwordx4 v251, s[98:99]
	s_add_u32 m0, s22, 0x2000
	v_mfma_f32_16x16x32_bf16 v[48:51], v[218:221], v[190:193], v[48:51]
	global_load_lds_dwordx4 v250, s[98:99]
	s_add_u32 m0, s22, 0x4000
	v_mfma_f32_16x16x32_bf16 v[44:47], v[186:189], v[222:225], v[44:47]
	global_load_lds_dwordx4 v249, s[98:99]
	s_add_u32 m0, s22, 0x6000
	v_mfma_f32_16x16x32_bf16 v[40:43], v[194:197], v[222:225], v[40:43]
	global_load_lds_dwordx4 v248, s[98:99]
	s_add_u32 m0, s22, 0x8000
	v_mfma_f32_16x16x32_bf16 v[36:39], v[198:201], v[222:225], v[36:39]
	global_load_lds_dwordx4 v247, s[100:101]
	s_add_u32 m0, s22, 0xa000
	v_mfma_f32_16x16x32_bf16 v[32:35], v[218:221], v[222:225], v[32:35]
	global_load_lds_dwordx4 v246, s[100:101]
	s_add_u32 m0, s22, 0xc000
	v_mfma_f32_16x16x32_bf16 v[28:31], v[186:189], v[226:229], v[28:31]
	global_load_lds_dwordx4 v245, s[100:101]
	s_add_u32 m0, s22, 0xe000
	v_mfma_f32_16x16x32_bf16 v[24:27], v[194:197], v[226:229], v[24:27]
	global_load_lds_dwordx4 v244, s[100:101]
	v_mfma_f32_16x16x32_bf16 v[20:23], v[198:201], v[226:229], v[20:23]
	s_add_u32 s98, s98, 0x80
	s_addc_u32 s99, s99, 0
	s_add_u32 s100, s100, 0x80
	s_addc_u32 s101, s101, 0
	v_mfma_f32_16x16x32_bf16 v[16:19], v[218:221], v[226:229], v[16:19]
	v_mfma_f32_16x16x32_bf16 v[12:15], v[186:189], v[230:233], v[12:15]
	v_mfma_f32_16x16x32_bf16 v[8:11], v[194:197], v[230:233], v[8:11]
	v_mfma_f32_16x16x32_bf16 v[4:7], v[198:201], v[230:233], v[4:7]
	v_mfma_f32_16x16x32_bf16 v[0:3], v[218:221], v[230:233], v[0:3]
	s_branch .Lg_rot589_main
.Lg_rot589_ehead:
	v_mfma_f32_16x16x32_bf16 v[60:63], v[186:189], v[190:193], v[60:63]
	s_add_u32 s98, s98, 0x80
	s_addc_u32 s99, s99, 0
	s_add_u32 s100, s100, 0x80
	s_addc_u32 s101, s101, 0
	v_mfma_f32_16x16x32_bf16 v[56:59], v[194:197], v[190:193], v[56:59]
	v_mfma_f32_16x16x32_bf16 v[52:55], v[198:201], v[190:193], v[52:55]
	v_mfma_f32_16x16x32_bf16 v[48:51], v[218:221], v[190:193], v[48:51]
	v_mfma_f32_16x16x32_bf16 v[44:47], v[186:189], v[222:225], v[44:47]
	v_mfma_f32_16x16x32_bf16 v[40:43], v[194:197], v[222:225], v[40:43]
	v_mfma_f32_16x16x32_bf16 v[36:39], v[198:201], v[222:225], v[36:39]
	v_mfma_f32_16x16x32_bf16 v[32:35], v[218:221], v[222:225], v[32:35]
	v_mfma_f32_16x16x32_bf16 v[28:31], v[186:189], v[226:229], v[28:31]
	v_mfma_f32_16x16x32_bf16 v[24:27], v[194:197], v[226:229], v[24:27]
	v_mfma_f32_16x16x32_bf16 v[20:23], v[198:201], v[226:229], v[20:23]
	v_mfma_f32_16x16x32_bf16 v[16:19], v[218:221], v[226:229], v[16:19]
	v_mfma_f32_16x16x32_bf16 v[12:15], v[186:189], v[230:233], v[12:15]
	v_mfma_f32_16x16x32_bf16 v[8:11], v[194:197], v[230:233], v[8:11]
	v_mfma_f32_16x16x32_bf16 v[4:7], v[198:201], v[230:233], v[4:7]
	v_mfma_f32_16x16x32_bf16 v[0:3], v[218:221], v[230:233], v[0:3]
	s_branch .Lg_rot589_main
.Lg_rot589_first:
	v_add_u32_e32 v174, s13, v136
	s_xor_b32 s22, s21, 0x10000
	v_add_u32_e32 v176, 64, v174
	v_add_u32_e32 v179, s22, v128
	v_ashrrev_i32_e32 v177, 31, v176
	v_lshlrev_b64 v[176:177], 1, v[176:177]
	v_readfirstlane_b32 s22, v179
	v_lshl_add_u64 v[180:181], s[0:1], 0, v[176:177]
	s_mov_b32 m0, s22
	v_add_u32_e32 v182, 0x2000, v179
	global_load_lds_dwordx4 v[180:181], off
	v_subrev_u32_e32 v251, s0, v180
	v_add_u32_e32 v180, 0x10040, v174
	v_ashrrev_i32_e32 v181, 31, v180
	v_lshlrev_b64 v[180:181], 1, v[180:181]
	v_readfirstlane_b32 s22, v182
	v_lshl_add_u64 v[184:185], s[0:1], 0, v[180:181]
	s_mov_b32 m0, s22
	v_add_u32_e32 v175, 0x4000, v179
	global_load_lds_dwordx4 v[184:185], off
	v_subrev_u32_e32 v250, s0, v184
	v_add_u32_e32 v184, 0x20040, v174
	v_ashrrev_i32_e32 v185, 31, v184
	v_lshlrev_b64 v[184:185], 1, v[184:185]
	v_readfirstlane_b32 s22, v175
	v_lshl_add_u64 v[182:183], s[0:1], 0, v[184:185]
	s_mov_b32 m0, s22
	v_add_u32_e32 v217, 0x6000, v179
	global_load_lds_dwordx4 v[182:183], off
	v_subrev_u32_e32 v249, s0, v182
	v_add_u32_e32 v182, 0x30040, v174
	v_ashrrev_i32_e32 v183, 31, v182
	v_lshlrev_b64 v[182:183], 1, v[182:183]
	v_readfirstlane_b32 s22, v217
	v_lshl_add_u64 v[174:175], s[0:1], 0, v[182:183]
	s_mov_b32 m0, s22
	v_lshl_add_u64 v[176:177], s[4:5], 0, v[176:177]
	global_load_lds_dwordx4 v[174:175], off
	v_subrev_u32_e32 v248, s0, v174
	v_add_u32_e32 v174, 0x8000, v179
	s_nop 0
	v_readfirstlane_b32 s22, v174
	s_mov_b32 m0, s22
	s_nop 0
	global_load_lds_dwordx4 v[176:177], off
	v_subrev_u32_e32 v247, s4, v176
	v_lshl_add_u64 v[176:177], s[4:5], 0, v[180:181]
	v_add_u32_e32 v180, 0xa000, v179
	s_nop 0
	v_readfirstlane_b32 s22, v180
	v_add_u32_e32 v180, 0xc000, v179
	s_mov_b32 m0, s22
	v_readfirstlane_b32 s22, v180
	v_add_u32_e32 v179, 0xe000, v179
	global_load_lds_dwordx4 v[176:177], off
	v_subrev_u32_e32 v246, s4, v176
	v_lshl_add_u64 v[176:177], s[4:5], 0, v[184:185]
	s_mov_b32 m0, s22
	v_readfirstlane_b32 s22, v179
	global_load_lds_dwordx4 v[176:177], off
	v_subrev_u32_e32 v245, s4, v176
	v_lshl_add_u64 v[176:177], s[4:5], 0, v[182:183]
	s_mov_b32 m0, s22
	s_nop 0
	global_load_lds_dwordx4 v[176:177], off
	v_subrev_u32_e32 v244, s4, v176
	s_add_u32 s98, s0, 0x80
	s_addc_u32 s99, s1, 0
	s_add_u32 s100, s4, 0x80
	s_addc_u32 s101, s5, 0
	v_readfirstlane_b32 s26, v179
	s_bfe_u32 s26, s26, 0x1000a
	s_branch .Lg_rot589_main

; #define LDB_(dst, ks) _Pragma("unroll") for (int n = 0; n < 4; ++n) dst[n] = *(const bf16x8*)(sB + b_off + n * 2048 + (ks) * 1024)
; #define LDA_(dst, ks, h) _Pragma("unroll") for (int m = 0; m < 4; ++m) dst[m] = *(const bf16x8*)(sA + a_off + ((h) * 4 + m) * 2048 + (ks) * 1024)
; #define MMA_(A, B, h) _Pragma("unroll") for (int m = 0; m < 4; ++m) _Pragma("unroll") for (int n = 0; n < 4; ++n) \
;       acc[(h) * 4 + m][n] = SWAP ? MFMA16(B[n], A[m], acc[(h) * 4 + m][n]) : MFMA16(A[m], B[n], acc[(h) * 4 + m][n])
; template <int MF, int NF, bool SWAP = true>
; DI void gemm_main(f32x4 (&acc)[MF][NF], const u16* __restrict__ Ab, int lda, const u16* __restrict__ Bb, int ldb,
;                   int K, char* shm) {
;     ...
;       LDB_(B0, 0); LDA_(A0, 0, 0);
;       LDA_(A1, 0, 1); MMA_(A0, B0, 0);
;       LDB_(B1, 1); LDA_(A2, 1, 0); MMA_(A1, B0, 1);
.Lg_rot589_main:
	s_waitcnt lgkmcnt(4)
	v_mfma_f32_16x16x32_bf16 v[124:127], v[138:141], v[154:157], v[124:127]
	v_mfma_f32_16x16x32_bf16 v[120:123], v[142:145], v[154:157], v[120:123]
	v_mfma_f32_16x16x32_bf16 v[116:119], v[146:149], v[154:157], v[116:119]
	v_mfma_f32_16x16x32_bf16 v[112:115], v[150:153], v[154:157], v[112:115]
	ds_read_b128 v[154:157], v137 offset:10240
	s_waitcnt lgkmcnt(4)
	v_mfma_f32_16x16x32_bf16 v[108:111], v[138:141], v[158:161], v[108:111]
	v_mfma_f32_16x16x32_bf16 v[104:107], v[142:145], v[158:161], v[104:107]
	v_mfma_f32_16x16x32_bf16 v[100:103], v[146:149], v[158:161], v[100:103]
	v_mfma_f32_16x16x32_bf16 v[96:99], v[150:153], v[158:161], v[96:99]
	ds_read_b128 v[158:161], v137 offset:12288
	s_waitcnt lgkmcnt(4)
	v_mfma_f32_16x16x32_bf16 v[92:95], v[138:141], v[162:165], v[92:95]
	v_mfma_f32_16x16x32_bf16 v[88:91], v[142:145], v[162:165], v[88:91]
	v_mfma_f32_16x16x32_bf16 v[84:87], v[146:149], v[162:165], v[84:87]
	v_mfma_f32_16x16x32_bf16 v[80:83], v[150:153], v[162:165], v[80:83]
	ds_read_b128 v[162:165], v137 offset:14336
	s_waitcnt lgkmcnt(4)
	v_mfma_f32_16x16x32_bf16 v[76:79], v[138:141], v[166:169], v[76:79]
	v_mfma_f32_16x16x32_bf16 v[72:75], v[142:145], v[166:169], v[72:75]
	v_mfma_f32_16x16x32_bf16 v[68:71], v[146:149], v[166:169], v[68:71]
	v_mfma_f32_16x16x32_bf16 v[64:67], v[150:153], v[166:169], v[64:67]
	s_waitcnt lgkmcnt(0)
	s_cmp_eq_u32 s26, 0
	s_cbranch_scc1 .Lg_rot589_mbar
	s_cmp_gt_u32 s15, 14
	s_cbranch_scc1 .Lg_rot589_mw0
	s_waitcnt vmcnt(8)
	s_branch .Lg_rot589_mbar

; #define LDB_(dst, ks) _Pragma("unroll") for (int n = 0; n < 4; ++n) dst[n] = *(const bf16x8*)(sB + b_off + n * 2048 + (ks) * 1024)
; #define LDA_(dst, ks, h) _Pragma("unroll") for (int m = 0; m < 4; ++m) dst[m] = *(const bf16x8*)(sA + a_off + ((h) * 4 + m) * 2048 + (ks) * 1024)
; #define MMA_(A, B, h) _Pragma("unroll") for (int m = 0; m < 4; ++m) _Pragma("unroll") for (int n = 0; n < 4; ++n) \
;       acc[(h) * 4 + m][n] = SWAP ? MFMA16(B[n], A[m], acc[(h) * 4 + m][n]) : MFMA16(A[m], B[n], acc[(h) * 4 + m][n])
; template <int MF, int NF, bool SWAP = true>
; DI void gemm_main(f32x4 (&acc)[MF][NF], const u16* __restrict__ Ab, int lda, const u16* __restrict__ Bb, int ldb,
;                   int K, char* shm) {
;     ...
;       LDB_(B1, 1); LDA_(A2, 1, 0); MMA_(A1, B0, 1);
;       LDA_(A3, 1, 1); MMA_(A2, B1, 0);
;       MMA_(A3, B1, 1);
.Lg_rot589_mbar:
	s_barrier
	s_cmp_lg_u32 s26, 0
	s_cbranch_scc1 .Lg_rot589_bplain
	s_cmp_gt_u32 s15, 13
	s_cbranch_scc1 .Lg_rot589_bplain
	ds_read_b128 v[186:189], v178 offset:33792
	v_mfma_f32_16x16x32_bf16 v[60:63], v[138:141], v[170:173], v[60:63]
	v_add_u32_e32 v255, s21, v128
	s_nop 0
	v_readfirstlane_b32 s22, v255
	s_nop 1
	s_add_u32 m0, s22, 0x0
	v_mfma_f32_16x16x32_bf16 v[56:59], v[142:145], v[170:173], v[56:59]
	global_load_lds_dwordx4 v251, s[98:99]
	s_add_u32 m0, s22, 0x2000
	ds_read_b128 v[194:197], v178 offset:35840
	v_mfma_f32_16x16x32_bf16 v[52:55], v[146:149], v[170:173], v[52:55]
	global_load_lds_dwordx4 v250, s[98:99]
	s_add_u32 m0, s22, 0x4000
	v_mfma_f32_16x16x32_bf16 v[48:51], v[150:153], v[170:173], v[48:51]
	global_load_lds_dwordx4 v249, s[98:99]
	s_add_u32 m0, s22, 0x6000
	ds_read_b128 v[198:201], v178 offset:37888
	v_mfma_f32_16x16x32_bf16 v[44:47], v[138:141], v[154:157], v[44:47]
	global_load_lds_dwordx4 v248, s[98:99]
	s_add_u32 m0, s22, 0x8000
	v_mfma_f32_16x16x32_bf16 v[40:43], v[142:145], v[154:157], v[40:43]
	global_load_lds_dwordx4 v247, s[100:101]
	s_add_u32 m0, s22, 0xa000
	ds_read_b128 v[218:221], v178 offset:39936
	v_mfma_f32_16x16x32_bf16 v[36:39], v[146:149], v[154:157], v[36:39]
	global_load_lds_dwordx4 v246, s[100:101]
	s_add_u32 m0, s22, 0xc000
	v_mfma_f32_16x16x32_bf16 v[32:35], v[150:153], v[154:157], v[32:35]
	global_load_lds_dwordx4 v245, s[100:101]
	s_add_u32 m0, s22, 0xe000
	ds_read_b128 v[154:157], v137 offset:1024
	v_mfma_f32_16x16x32_bf16 v[28:31], v[138:141], v[158:161], v[28:31]
	global_load_lds_dwordx4 v244, s[100:101]
	v_mfma_f32_16x16x32_bf16 v[24:27], v[142:145], v[158:161], v[24:27]
	ds_read_b128 v[182:185], v137 offset:3072
	v_mfma_f32_16x16x32_bf16 v[20:23], v[146:149], v[158:161], v[20:23]
	v_mfma_f32_16x16x32_bf16 v[16:19], v[150:153], v[158:161], v[16:19]
	ds_read_b128 v[158:161], v137 offset:5120
	v_mfma_f32_16x16x32_bf16 v[12:15], v[138:141], v[162:165], v[12:15]
	v_mfma_f32_16x16x32_bf16 v[8:11], v[142:145], v[162:165], v[8:11]
	ds_read_b128 v[138:141], v137 offset:7168
	v_mfma_f32_16x16x32_bf16 v[4:7], v[146:149], v[162:165], v[4:7]
	v_mfma_f32_16x16x32_bf16 v[0:3], v[150:153], v[162:165], v[0:3]
	ds_read_b128 v[190:193], v137 offset:9216
	s_waitcnt lgkmcnt(4)
	v_mfma_f32_16x16x32_bf16 v[124:127], v[186:189], v[154:157], v[124:127]
	v_mfma_f32_16x16x32_bf16 v[120:123], v[194:197], v[154:157], v[120:123]
	v_mfma_f32_16x16x32_bf16 v[116:119], v[198:201], v[154:157], v[116:119]
	v_mfma_f32_16x16x32_bf16 v[112:115], v[218:221], v[154:157], v[112:115]
	ds_read_b128 v[222:225], v137 offset:11264
	s_waitcnt lgkmcnt(4)
	v_mfma_f32_16x16x32_bf16 v[108:111], v[186:189], v[182:185], v[108:111]
	v_mfma_f32_16x16x32_bf16 v[104:107], v[194:197], v[182:185], v[104:107]
	v_mfma_f32_16x16x32_bf16 v[100:103], v[198:201], v[182:185], v[100:103]
	v_mfma_f32_16x16x32_bf16 v[96:99], v[218:221], v[182:185], v[96:99]
	ds_read_b128 v[226:229], v137 offset:13312
	s_waitcnt lgkmcnt(4)
	v_mfma_f32_16x16x32_bf16 v[92:95], v[186:189], v[158:161], v[92:95]
	v_mfma_f32_16x16x32_bf16 v[88:91], v[194:197], v[158:161], v[88:91]
	v_mfma_f32_16x16x32_bf16 v[84:87], v[198:201], v[158:161], v[84:87]
	v_mfma_f32_16x16x32_bf16 v[80:83], v[218:221], v[158:161], v[80:83]
	ds_read_b128 v[230:233], v137 offset:15360
	s_waitcnt lgkmcnt(4)
	v_mfma_f32_16x16x32_bf16 v[76:79], v[186:189], v[138:141], v[76:79]
	v_mfma_f32_16x16x32_bf16 v[72:75], v[194:197], v[138:141], v[72:75]
	v_mfma_f32_16x16x32_bf16 v[68:71], v[198:201], v[138:141], v[68:71]
	v_mfma_f32_16x16x32_bf16 v[64:67], v[218:221], v[138:141], v[64:67]
	s_waitcnt lgkmcnt(0)
	s_waitcnt vmcnt(8)
	s_branch .Lg_rot589_ectl
; #define LDB_(dst, ks) _Pragma("unroll") for (int n = 0; n < 4; ++n) dst[n] = *(const bf16x8*)(sB + b_off + n * 2048 + (ks) * 1024)
; #define LDA_(dst, ks, h) _Pragma("unroll") for (int m = 0; m < 4; ++m) dst[m] = *(const bf16x8*)(sA + a_off + ((h) * 4 + m) * 2048 + (ks) * 1024)
; #define MMA_(A, B, h) _Pragma("unroll") for (int m = 0; m < 4; ++m) _Pragma("unroll") for (int n = 0; n < 4; ++n) \
;       acc[(h) * 4 + m][n] = SWAP ? MFMA16(B[n], A[m], acc[(h) * 4 + m][n]) : MFMA16(A[m], B[n], acc[(h) * 4 + m][n])
; template <int MF, int NF, bool SWAP = true>
; DI void gemm_main(f32x4 (&acc)[MF][NF], const u16* __restrict__ Ab, int lda, const u16* __restrict__ Bb, int ldb,
;                   int K, char* shm) {
;     ...
;       LDB_(B1, 1); LDA_(A2, 1, 0); MMA_(A1, B0, 1);
;       LDA_(A3, 1, 1); MMA_(A2, B1, 0);
;       MMA_(A3, B1, 1);
;     ...
;     if constexpr (RING3) {
;       if (t + 2 < nt) asm volatile("s_waitcnt vmcnt(6)" ::: "memory");
;       else asm volatile("s_waitcnt vmcnt(0)" ::: "memory");
;       asm volatile("s_waitcnt lgkmcnt(0)" ::: "memory");
;       __builtin_amdgcn_s_barrier();
;       cur3 = (cur3 == 2) ? 0 : cur3 + 1;
;       nxt3 = (nxt3 == 2) ? 0 : nxt3 + 1;
;     } else {
;       asm volatile("s_waitcnt vmcnt(0)" ::: "memory");
;       __syncthreads();
;     }
.Lg_rot589_bplain:
	ds_read_b128 v[186:189], v178 offset:33792
	v_mfma_f32_16x16x32_bf16 v[60:63], v[138:141], v[170:173], v[60:63]
	v_mfma_f32_16x16x32_bf16 v[56:59], v[142:145], v[170:173], v[56:59]
	ds_read_b128 v[194:197], v178 offset:35840
	v_mfma_f32_16x16x32_bf16 v[52:55], v[146:149], v[170:173], v[52:55]
	v_mfma_f32_16x16x32_bf16 v[48:51], v[150:153], v[170:173], v[48:51]
	ds_read_b128 v[198:201], v178 offset:37888
	v_mfma_f32_16x16x32_bf16 v[44:47], v[138:141], v[154:157], v[44:47]
	v_mfma_f32_16x16x32_bf16 v[40:43], v[142:145], v[154:157], v[40:43]
	ds_read_b128 v[218:221], v178 offset:39936
	v_mfma_f32_16x16x32_bf16 v[36:39], v[146:149], v[154:157], v[36:39]
	v_mfma_f32_16x16x32_bf16 v[32:35], v[150:153], v[154:157], v[32:35]
	ds_read_b128 v[154:157], v137 offset:1024
	v_mfma_f32_16x16x32_bf16 v[28:31], v[138:141], v[158:161], v[28:31]
	v_mfma_f32_16x16x32_bf16 v[24:27], v[142:145], v[158:161], v[24:27]
	ds_read_b128 v[182:185], v137 offset:3072
	v_mfma_f32_16x16x32_bf16 v[20:23], v[146:149], v[158:161], v[20:23]
	v_mfma_f32_16x16x32_bf16 v[16:19], v[150:153], v[158:161], v[16:19]
	ds_read_b128 v[158:161], v137 offset:5120
	v_mfma_f32_16x16x32_bf16 v[12:15], v[138:141], v[162:165], v[12:15]
	v_mfma_f32_16x16x32_bf16 v[8:11], v[142:145], v[162:165], v[8:11]
	ds_read_b128 v[138:141], v137 offset:7168
	v_mfma_f32_16x16x32_bf16 v[4:7], v[146:149], v[162:165], v[4:7]
	v_mfma_f32_16x16x32_bf16 v[0:3], v[150:153], v[162:165], v[0:3]
	ds_read_b128 v[190:193], v137 offset:9216
	s_waitcnt lgkmcnt(4)
	v_mfma_f32_16x16x32_bf16 v[124:127], v[186:189], v[154:157], v[124:127]
	v_mfma_f32_16x16x32_bf16 v[120:123], v[194:197], v[154:157], v[120:123]
	v_mfma_f32_16x16x32_bf16 v[116:119], v[198:201], v[154:157], v[116:119]
	v_mfma_f32_16x16x32_bf16 v[112:115], v[218:221], v[154:157], v[112:115]
	ds_read_b128 v[222:225], v137 offset:11264
	s_waitcnt lgkmcnt(4)
	v_mfma_f32_16x16x32_bf16 v[108:111], v[186:189], v[182:185], v[108:111]
	v_mfma_f32_16x16x32_bf16 v[104:107], v[194:197], v[182:185], v[104:107]
	v_mfma_f32_16x16x32_bf16 v[100:103], v[198:201], v[182:185], v[100:103]
	v_mfma_f32_16x16x32_bf16 v[96:99], v[218:221], v[182:185], v[96:99]
	ds_read_b128 v[226:229], v137 offset:13312
	s_waitcnt lgkmcnt(4)
	v_mfma_f32_16x16x32_bf16 v[92:95], v[186:189], v[158:161], v[92:95]
	v_mfma_f32_16x16x32_bf16 v[88:91], v[194:197], v[158:161], v[88:91]
	v_mfma_f32_16x16x32_bf16 v[84:87], v[198:201], v[158:161], v[84:87]
	v_mfma_f32_16x16x32_bf16 v[80:83], v[218:221], v[158:161], v[80:83]
	ds_read_b128 v[230:233], v137 offset:15360
	s_waitcnt lgkmcnt(4)
	v_mfma_f32_16x16x32_bf16 v[76:79], v[186:189], v[138:141], v[76:79]
	v_mfma_f32_16x16x32_bf16 v[72:75], v[194:197], v[138:141], v[72:75]
	v_mfma_f32_16x16x32_bf16 v[68:71], v[198:201], v[138:141], v[68:71]
	v_mfma_f32_16x16x32_bf16 v[64:67], v[218:221], v[138:141], v[64:67]
	s_waitcnt lgkmcnt(0)
	s_cmp_lg_u32 s26, 0
	s_cbranch_scc1 .Lg_rot589_ectl
	s_waitcnt vmcnt(0)
.Lg_rot589_ectl:
	s_add_i32 s13, s13, 64
	s_add_i32 s16, s16, 0x10000
	s_add_i32 s15, s15, 1
	s_cmpk_lg_i32 s13, 0x400
	s_barrier
	s_cbranch_scc1 .LBB0_589
	v_mfma_f32_16x16x32_bf16 v[60:63], v[186:189], v[190:193], v[60:63]
	v_mfma_f32_16x16x32_bf16 v[56:59], v[194:197], v[190:193], v[56:59]
	v_mfma_f32_16x16x32_bf16 v[52:55], v[198:201], v[190:193], v[52:55]
	v_mfma_f32_16x16x32_bf16 v[48:51], v[218:221], v[190:193], v[48:51]
	v_mfma_f32_16x16x32_bf16 v[44:47], v[186:189], v[222:225], v[44:47]
	v_mfma_f32_16x16x32_bf16 v[40:43], v[194:197], v[222:225], v[40:43]
	v_mfma_f32_16x16x32_bf16 v[36:39], v[198:201], v[222:225], v[36:39]
	v_mfma_f32_16x16x32_bf16 v[32:35], v[218:221], v[222:225], v[32:35]
	v_mfma_f32_16x16x32_bf16 v[28:31], v[186:189], v[226:229], v[28:31]
	v_mfma_f32_16x16x32_bf16 v[24:27], v[194:197], v[226:229], v[24:27]
	v_mfma_f32_16x16x32_bf16 v[20:23], v[198:201], v[226:229], v[20:23]
	v_mfma_f32_16x16x32_bf16 v[16:19], v[218:221], v[226:229], v[16:19]
	v_mfma_f32_16x16x32_bf16 v[12:15], v[186:189], v[230:233], v[12:15]
	v_mfma_f32_16x16x32_bf16 v[8:11], v[194:197], v[230:233], v[8:11]
	v_mfma_f32_16x16x32_bf16 v[4:7], v[198:201], v[230:233], v[4:7]
	v_mfma_f32_16x16x32_bf16 v[0:3], v[218:221], v[230:233], v[0:3]
	s_nop 7
	s_nop 1

; #define LDB_(dst, ks) _Pragma("unroll") for (int n = 0; n < 4; ++n) dst[n] = *(const bf16x8*)(sB + b_off + n * 2048 + (ks) * 1024)
; #define LDA_(dst, ks, h) _Pragma("unroll") for (int m = 0; m < 4; ++m) dst[m] = *(const bf16x8*)(sA + a_off + ((h) * 4 + m) * 2048 + (ks) * 1024)
; #define MMA_(A, B, h) _Pragma("unroll") for (int m = 0; m < 4; ++m) _Pragma("unroll") for (int n = 0; n < 4; ++n) \
;       acc[(h) * 4 + m][n] = SWAP ? MFMA16(B[n], A[m], acc[(h) * 4 + m][n]) : MFMA16(A[m], B[n], acc[(h) * 4 + m][n])
; template <int MF, int NF, bool SWAP = true>
; DI void gemm_main(f32x4 (&acc)[MF][NF], const u16* __restrict__ Ab, int lda, const u16* __restrict__ Bb, int ldb,
;                   int K, char* shm) {
;     ...
;   for (int t = 0; t < nt; ++t) {
;     const int cur = RING3 ? cur3 : (t & 1);
;     if constexpr (RING3) {
;       if (t + 2 < nt) G_STAGE(nxt3, t + 2);
;     } else {
;       if (t + 1 < nt) G_STAGE(cur ^ 1, t + 1);
;     }
;     const char* sA = shm + cur * STAGE;
;     const char* sB = sA + TILE_A;
;     if constexpr (MF == 8 && NF == 4) {
;       bf16x8 B0[4], B1[4], A0[4], A1[4], A2[4], A3[4];
;     ...
;       LDB_(B0, 0); LDA_(A0, 0, 0);
;       LDA_(A1, 0, 1); MMA_(A0, B0, 0);
;       LDB_(B1, 1); LDA_(A2, 1, 0); MMA_(A1, B0, 1);
;       LDA_(A3, 1, 1); MMA_(A2, B1, 0);
;       MMA_(A3, B1, 1);
.LBB0_819:
	s_and_b32 s19, s17, 0x10000
	v_add_u32_e32 v137, s19, v132
	v_add_u32_e32 v178, v137, v131
	ds_read_b128 v[138:141], v178 offset:32768
	ds_read_b128 v[142:145], v178 offset:34816
	ds_read_b128 v[146:149], v178 offset:36864
	ds_read_b128 v[150:153], v178 offset:38912
	v_add_u32_e32 v137, v137, v130
	ds_read_b128 v[154:157], v137
	ds_read_b128 v[158:161], v137 offset:2048
	ds_read_b128 v[162:165], v137 offset:4096
	ds_read_b128 v[166:169], v137 offset:6144
	ds_read_b128 v[170:173], v137 offset:8192
	s_cmp_gt_u32 s18, 2
	s_cbranch_scc1 .Lg_rot819_last
	s_cmp_eq_u32 s18, 0
	s_cbranch_scc1 .Lg_rot819_first
	s_cmp_lg_u32 s26, 0
	s_cbranch_scc0 .Lg_rot819_ehead
	v_mfma_f32_16x16x32_bf16 v[60:63], v[186:189], v[190:193], v[60:63]
	s_xor_b32 s20, s19, 0x10000
	v_add_u32_e32 v179, s20, v129
	v_mfma_f32_16x16x32_bf16 v[56:59], v[194:197], v[190:193], v[56:59]
	s_nop 0
	v_readfirstlane_b32 s20, v179
	s_nop 1
	s_add_u32 m0, s20, 0x0
	v_mfma_f32_16x16x32_bf16 v[52:55], v[198:201], v[190:193], v[52:55]
	global_load_lds_dwordx4 v251, s[98:99]
	s_add_u32 m0, s20, 0x2000
	v_mfma_f32_16x16x32_bf16 v[48:51], v[218:221], v[190:193], v[48:51]
	global_load_lds_dwordx4 v250, s[98:99]
	s_add_u32 m0, s20, 0x4000
	v_mfma_f32_16x16x32_bf16 v[44:47], v[186:189], v[222:225], v[44:47]
	global_load_lds_dwordx4 v249, s[98:99]
	s_add_u32 m0, s20, 0x6000
	v_mfma_f32_16x16x32_bf16 v[40:43], v[194:197], v[222:225], v[40:43]
	global_load_lds_dwordx4 v248, s[98:99]
	s_add_u32 m0, s20, 0x8000
	v_mfma_f32_16x16x32_bf16 v[36:39], v[198:201], v[222:225], v[36:39]
	global_load_lds_dwordx4 v247, s[100:101]
	s_add_u32 m0, s20, 0xa000
	v_mfma_f32_16x16x32_bf16 v[32:35], v[218:221], v[222:225], v[32:35]
	global_load_lds_dwordx4 v246, s[100:101]
	s_add_u32 m0, s20, 0xc000
	v_mfma_f32_16x16x32_bf16 v[28:31], v[186:189], v[226:229], v[28:31]
	global_load_lds_dwordx4 v245, s[100:101]
	s_add_u32 m0, s20, 0xe000
	v_mfma_f32_16x16x32_bf16 v[24:27], v[194:197], v[226:229], v[24:27]
	global_load_lds_dwordx4 v244, s[100:101]
	v_mfma_f32_16x16x32_bf16 v[20:23], v[198:201], v[226:229], v[20:23]
	s_add_u32 s98, s98, 0x80
	s_addc_u32 s99, s99, 0
	s_add_u32 s100, s100, 0x80
	s_addc_u32 s101, s101, 0
	v_mfma_f32_16x16x32_bf16 v[16:19], v[218:221], v[226:229], v[16:19]
	v_mfma_f32_16x16x32_bf16 v[8:11], v[186:189], v[230:233], v[8:11]
	v_mfma_f32_16x16x32_bf16 v[4:7], v[194:197], v[230:233], v[4:7]
	v_mfma_f32_16x16x32_bf16 v[0:3], v[198:201], v[230:233], v[0:3]
	v_mfma_f32_16x16x32_bf16 v[12:15], v[218:221], v[230:233], v[12:15]
	s_branch .Lg_rot819_main
.Lg_rot819_ehead:
	v_mfma_f32_16x16x32_bf16 v[60:63], v[186:189], v[190:193], v[60:63]
	s_add_u32 s98, s98, 0x80
	s_addc_u32 s99, s99, 0
	s_add_u32 s100, s100, 0x80
	s_addc_u32 s101, s101, 0
	v_mfma_f32_16x16x32_bf16 v[56:59], v[194:197], v[190:193], v[56:59]
	v_mfma_f32_16x16x32_bf16 v[52:55], v[198:201], v[190:193], v[52:55]
	v_mfma_f32_16x16x32_bf16 v[48:51], v[218:221], v[190:193], v[48:51]
	v_mfma_f32_16x16x32_bf16 v[44:47], v[186:189], v[222:225], v[44:47]
	v_mfma_f32_16x16x32_bf16 v[40:43], v[194:197], v[222:225], v[40:43]
	v_mfma_f32_16x16x32_bf16 v[36:39], v[198:201], v[222:225], v[36:39]
	v_mfma_f32_16x16x32_bf16 v[32:35], v[218:221], v[222:225], v[32:35]
	v_mfma_f32_16x16x32_bf16 v[28:31], v[186:189], v[226:229], v[28:31]
	v_mfma_f32_16x16x32_bf16 v[24:27], v[194:197], v[226:229], v[24:27]
	v_mfma_f32_16x16x32_bf16 v[20:23], v[198:201], v[226:229], v[20:23]
	v_mfma_f32_16x16x32_bf16 v[16:19], v[218:221], v[226:229], v[16:19]
	v_mfma_f32_16x16x32_bf16 v[8:11], v[186:189], v[230:233], v[8:11]
	v_mfma_f32_16x16x32_bf16 v[4:7], v[194:197], v[230:233], v[4:7]
	v_mfma_f32_16x16x32_bf16 v[0:3], v[198:201], v[230:233], v[0:3]
	v_mfma_f32_16x16x32_bf16 v[12:15], v[218:221], v[230:233], v[12:15]
	s_branch .Lg_rot819_main
.Lg_rot819_first:
	v_add_u32_e32 v174, s1, v136
	s_xor_b32 s20, s19, 0x10000
	v_add_u32_e32 v176, 64, v174
	v_add_u32_e32 v179, s20, v129
	v_ashrrev_i32_e32 v177, 31, v176
	v_lshlrev_b64 v[176:177], 1, v[176:177]
	v_readfirstlane_b32 s20, v179
	v_lshl_add_u64 v[180:181], s[6:7], 0, v[176:177]
	s_mov_b32 m0, s20
	v_add_u32_e32 v182, 0x2000, v179
	global_load_lds_dwordx4 v[180:181], off
	v_subrev_u32_e32 v251, s6, v180
	v_add_u32_e32 v180, 0x8040, v174
	v_ashrrev_i32_e32 v181, 31, v180
	v_lshlrev_b64 v[180:181], 1, v[180:181]
	v_readfirstlane_b32 s20, v182
	v_lshl_add_u64 v[184:185], s[6:7], 0, v[180:181]
	s_mov_b32 m0, s20
	v_add_u32_e32 v175, 0x4000, v179
	global_load_lds_dwordx4 v[184:185], off
	v_subrev_u32_e32 v250, s6, v184
	v_add_u32_e32 v184, 0x10040, v174
	v_ashrrev_i32_e32 v185, 31, v184
	v_lshlrev_b64 v[184:185], 1, v[184:185]
	v_readfirstlane_b32 s20, v175
	v_lshl_add_u64 v[182:183], s[6:7], 0, v[184:185]
	s_mov_b32 m0, s20
	v_add_u32_e32 v217, 0x6000, v179
	global_load_lds_dwordx4 v[182:183], off
	v_subrev_u32_e32 v249, s6, v182
	v_add_u32_e32 v182, 0x18040, v174
	v_ashrrev_i32_e32 v183, 31, v182
	v_lshlrev_b64 v[182:183], 1, v[182:183]
	v_readfirstlane_b32 s20, v217
	v_lshl_add_u64 v[174:175], s[6:7], 0, v[182:183]
	s_mov_b32 m0, s20
	v_lshl_add_u64 v[176:177], s[8:9], 0, v[176:177]
	global_load_lds_dwordx4 v[174:175], off
	v_subrev_u32_e32 v248, s6, v174
	v_add_u32_e32 v174, 0x8000, v179
	s_nop 0
	v_readfirstlane_b32 s20, v174
	s_mov_b32 m0, s20
	s_nop 0
	global_load_lds_dwordx4 v[176:177], off
	v_subrev_u32_e32 v247, s8, v176
	v_lshl_add_u64 v[176:177], s[8:9], 0, v[180:181]
	v_add_u32_e32 v180, 0xa000, v179
	s_nop 0
	v_readfirstlane_b32 s20, v180
	v_add_u32_e32 v180, 0xc000, v179
	s_mov_b32 m0, s20
	v_readfirstlane_b32 s20, v180
	v_add_u32_e32 v179, 0xe000, v179
	global_load_lds_dwordx4 v[176:177], off
	v_subrev_u32_e32 v246, s8, v176
	v_lshl_add_u64 v[176:177], s[8:9], 0, v[184:185]
	s_mov_b32 m0, s20
	v_readfirstlane_b32 s20, v179
	global_load_lds_dwordx4 v[176:177], off
	v_subrev_u32_e32 v245, s8, v176
	v_lshl_add_u64 v[176:177], s[8:9], 0, v[182:183]
	s_mov_b32 m0, s20
	s_nop 0
	global_load_lds_dwordx4 v[176:177], off
	v_subrev_u32_e32 v244, s8, v176
	s_add_u32 s98, s6, 0x80
	s_addc_u32 s99, s7, 0
	s_add_u32 s100, s8, 0x80
	s_addc_u32 s101, s9, 0
	v_readfirstlane_b32 s26, v179
	s_bfe_u32 s26, s26, 0x1000a
	s_branch .Lg_rot819_main

; #define LDB_(dst, ks) _Pragma("unroll") for (int n = 0; n < 4; ++n) dst[n] = *(const bf16x8*)(sB + b_off + n * 2048 + (ks) * 1024)
; #define LDA_(dst, ks, h) _Pragma("unroll") for (int m = 0; m < 4; ++m) dst[m] = *(const bf16x8*)(sA + a_off + ((h) * 4 + m) * 2048 + (ks) * 1024)
; #define MMA_(A, B, h) _Pragma("unroll") for (int m = 0; m < 4; ++m) _Pragma("unroll") for (int n = 0; n < 4; ++n) \
;       acc[(h) * 4 + m][n] = SWAP ? MFMA16(B[n], A[m], acc[(h) * 4 + m][n]) : MFMA16(A[m], B[n], acc[(h) * 4 + m][n])
; template <int MF, int NF, bool SWAP = true>
; DI void gemm_main(f32x4 (&acc)[MF][NF], const u16* __restrict__ Ab, int lda, const u16* __restrict__ Bb, int ldb,
;                   int K, char* shm) {
;     ...
;       LDB_(B0, 0); LDA_(A0, 0, 0);
;       LDA_(A1, 0, 1); MMA_(A0, B0, 0);
;       LDB_(B1, 1); LDA_(A2, 1, 0); MMA_(A1, B0, 1);
.Lg_rot819_main:
	s_waitcnt lgkmcnt(4)
	v_mfma_f32_16x16x32_bf16 v[124:127], v[138:141], v[154:157], v[124:127]
	v_mfma_f32_16x16x32_bf16 v[120:123], v[142:145], v[154:157], v[120:123]
	v_mfma_f32_16x16x32_bf16 v[116:119], v[146:149], v[154:157], v[116:119]
	v_mfma_f32_16x16x32_bf16 v[112:115], v[150:153], v[154:157], v[112:115]
	ds_read_b128 v[154:157], v137 offset:10240
	s_waitcnt lgkmcnt(4)
	v_mfma_f32_16x16x32_bf16 v[108:111], v[138:141], v[158:161], v[108:111]
	v_mfma_f32_16x16x32_bf16 v[104:107], v[142:145], v[158:161], v[104:107]
	v_mfma_f32_16x16x32_bf16 v[100:103], v[146:149], v[158:161], v[100:103]
	v_mfma_f32_16x16x32_bf16 v[96:99], v[150:153], v[158:161], v[96:99]
	ds_read_b128 v[158:161], v137 offset:12288
	s_waitcnt lgkmcnt(4)
	v_mfma_f32_16x16x32_bf16 v[92:95], v[138:141], v[162:165], v[92:95]
	v_mfma_f32_16x16x32_bf16 v[88:91], v[142:145], v[162:165], v[88:91]
	v_mfma_f32_16x16x32_bf16 v[84:87], v[146:149], v[162:165], v[84:87]
	v_mfma_f32_16x16x32_bf16 v[80:83], v[150:153], v[162:165], v[80:83]
	ds_read_b128 v[162:165], v137 offset:14336
	s_waitcnt lgkmcnt(4)
	v_mfma_f32_16x16x32_bf16 v[76:79], v[138:141], v[166:169], v[76:79]
	v_mfma_f32_16x16x32_bf16 v[72:75], v[142:145], v[166:169], v[72:75]
	v_mfma_f32_16x16x32_bf16 v[68:71], v[146:149], v[166:169], v[68:71]
	v_mfma_f32_16x16x32_bf16 v[64:67], v[150:153], v[166:169], v[64:67]
	s_waitcnt lgkmcnt(0)
	s_cmp_eq_u32 s26, 0
	s_cbranch_scc1 .Lg_rot819_mbar
	s_cmp_gt_u32 s18, 2
	s_cbranch_scc1 .Lg_rot819_mw0
	s_waitcnt vmcnt(8)
	s_branch .Lg_rot819_mbar

; #define LDB_(dst, ks) _Pragma("unroll") for (int n = 0; n < 4; ++n) dst[n] = *(const bf16x8*)(sB + b_off + n * 2048 + (ks) * 1024)
; #define LDA_(dst, ks, h) _Pragma("unroll") for (int m = 0; m < 4; ++m) dst[m] = *(const bf16x8*)(sA + a_off + ((h) * 4 + m) * 2048 + (ks) * 1024)
; #define MMA_(A, B, h) _Pragma("unroll") for (int m = 0; m < 4; ++m) _Pragma("unroll") for (int n = 0; n < 4; ++n) \
;       acc[(h) * 4 + m][n] = SWAP ? MFMA16(B[n], A[m], acc[(h) * 4 + m][n]) : MFMA16(A[m], B[n], acc[(h) * 4 + m][n])
; template <int MF, int NF, bool SWAP = true>
; DI void gemm_main(f32x4 (&acc)[MF][NF], const u16* __restrict__ Ab, int lda, const u16* __restrict__ Bb, int ldb,
;                   int K, char* shm) {
;     ...
;       LDB_(B1, 1); LDA_(A2, 1, 0); MMA_(A1, B0, 1);
;       LDA_(A3, 1, 1); MMA_(A2, B1, 0);
;       MMA_(A3, B1, 1);
.Lg_rot819_mbar:
	s_barrier
	s_cmp_lg_u32 s26, 0
	s_cbranch_scc1 .Lg_rot819_bplain
	s_cmp_gt_u32 s18, 1
	s_cbranch_scc1 .Lg_rot819_bplain
	ds_read_b128 v[186:189], v178 offset:33792
	v_mfma_f32_16x16x32_bf16 v[60:63], v[138:141], v[170:173], v[60:63]
	v_add_u32_e32 v255, s19, v129
	s_nop 0
	v_readfirstlane_b32 s20, v255
	s_nop 1
	s_add_u32 m0, s20, 0x0
	v_mfma_f32_16x16x32_bf16 v[56:59], v[142:145], v[170:173], v[56:59]
	global_load_lds_dwordx4 v251, s[98:99]
	s_add_u32 m0, s20, 0x2000
	ds_read_b128 v[194:197], v178 offset:35840
	v_mfma_f32_16x16x32_bf16 v[52:55], v[146:149], v[170:173], v[52:55]
	global_load_lds_dwordx4 v250, s[98:99]
	s_add_u32 m0, s20, 0x4000
	v_mfma_f32_16x16x32_bf16 v[48:51], v[150:153], v[170:173], v[48:51]
	global_load_lds_dwordx4 v249, s[98:99]
	s_add_u32 m0, s20, 0x6000
	ds_read_b128 v[198:201], v178 offset:37888
	v_mfma_f32_16x16x32_bf16 v[44:47], v[138:141], v[154:157], v[44:47]
	global_load_lds_dwordx4 v248, s[98:99]
	s_add_u32 m0, s20, 0x8000
	v_mfma_f32_16x16x32_bf16 v[40:43], v[142:145], v[154:157], v[40:43]
	global_load_lds_dwordx4 v247, s[100:101]
	s_add_u32 m0, s20, 0xa000
	ds_read_b128 v[218:221], v178 offset:39936
	v_mfma_f32_16x16x32_bf16 v[36:39], v[146:149], v[154:157], v[36:39]
	global_load_lds_dwordx4 v246, s[100:101]
	s_add_u32 m0, s20, 0xc000
	v_mfma_f32_16x16x32_bf16 v[32:35], v[150:153], v[154:157], v[32:35]
	global_load_lds_dwordx4 v245, s[100:101]
	s_add_u32 m0, s20, 0xe000
	ds_read_b128 v[154:157], v137 offset:1024
	v_mfma_f32_16x16x32_bf16 v[28:31], v[138:141], v[158:161], v[28:31]
	global_load_lds_dwordx4 v244, s[100:101]
	v_mfma_f32_16x16x32_bf16 v[24:27], v[142:145], v[158:161], v[24:27]
	ds_read_b128 v[182:185], v137 offset:3072
	v_mfma_f32_16x16x32_bf16 v[20:23], v[146:149], v[158:161], v[20:23]
	v_mfma_f32_16x16x32_bf16 v[16:19], v[150:153], v[158:161], v[16:19]
	ds_read_b128 v[158:161], v137 offset:5120
	v_mfma_f32_16x16x32_bf16 v[8:11], v[138:141], v[162:165], v[8:11]
	v_mfma_f32_16x16x32_bf16 v[4:7], v[142:145], v[162:165], v[4:7]
	ds_read_b128 v[138:141], v137 offset:7168
	v_mfma_f32_16x16x32_bf16 v[0:3], v[146:149], v[162:165], v[0:3]
	v_mfma_f32_16x16x32_bf16 v[12:15], v[150:153], v[162:165], v[12:15]
	ds_read_b128 v[190:193], v137 offset:9216
	s_waitcnt lgkmcnt(4)
	v_mfma_f32_16x16x32_bf16 v[124:127], v[186:189], v[154:157], v[124:127]
	v_mfma_f32_16x16x32_bf16 v[120:123], v[194:197], v[154:157], v[120:123]
	v_mfma_f32_16x16x32_bf16 v[116:119], v[198:201], v[154:157], v[116:119]
	v_mfma_f32_16x16x32_bf16 v[112:115], v[218:221], v[154:157], v[112:115]
	ds_read_b128 v[222:225], v137 offset:11264
	s_waitcnt lgkmcnt(4)
	v_mfma_f32_16x16x32_bf16 v[108:111], v[186:189], v[182:185], v[108:111]
	v_mfma_f32_16x16x32_bf16 v[104:107], v[194:197], v[182:185], v[104:107]
	v_mfma_f32_16x16x32_bf16 v[100:103], v[198:201], v[182:185], v[100:103]
	v_mfma_f32_16x16x32_bf16 v[96:99], v[218:221], v[182:185], v[96:99]
	ds_read_b128 v[226:229], v137 offset:13312
	s_waitcnt lgkmcnt(4)
	v_mfma_f32_16x16x32_bf16 v[92:95], v[186:189], v[158:161], v[92:95]
	v_mfma_f32_16x16x32_bf16 v[88:91], v[194:197], v[158:161], v[88:91]
	v_mfma_f32_16x16x32_bf16 v[84:87], v[198:201], v[158:161], v[84:87]
	v_mfma_f32_16x16x32_bf16 v[80:83], v[218:221], v[158:161], v[80:83]
	ds_read_b128 v[230:233], v137 offset:15360
	s_waitcnt lgkmcnt(4)
	v_mfma_f32_16x16x32_bf16 v[76:79], v[186:189], v[138:141], v[76:79]
	v_mfma_f32_16x16x32_bf16 v[72:75], v[194:197], v[138:141], v[72:75]
	v_mfma_f32_16x16x32_bf16 v[68:71], v[198:201], v[138:141], v[68:71]
	v_mfma_f32_16x16x32_bf16 v[64:67], v[218:221], v[138:141], v[64:67]
	s_waitcnt lgkmcnt(0)
	s_waitcnt vmcnt(8)
	s_branch .Lg_rot819_ectl
; #define LDB_(dst, ks) _Pragma("unroll") for (int n = 0; n < 4; ++n) dst[n] = *(const bf16x8*)(sB + b_off + n * 2048 + (ks) * 1024)
; #define LDA_(dst, ks, h) _Pragma("unroll") for (int m = 0; m < 4; ++m) dst[m] = *(const bf16x8*)(sA + a_off + ((h) * 4 + m) * 2048 + (ks) * 1024)
; #define MMA_(A, B, h) _Pragma("unroll") for (int m = 0; m < 4; ++m) _Pragma("unroll") for (int n = 0; n < 4; ++n) \
;       acc[(h) * 4 + m][n] = SWAP ? MFMA16(B[n], A[m], acc[(h) * 4 + m][n]) : MFMA16(A[m], B[n], acc[(h) * 4 + m][n])
; template <int MF, int NF, bool SWAP = true>
; DI void gemm_main(f32x4 (&acc)[MF][NF], const u16* __restrict__ Ab, int lda, const u16* __restrict__ Bb, int ldb,
;                   int K, char* shm) {
;     ...
;       LDB_(B1, 1); LDA_(A2, 1, 0); MMA_(A1, B0, 1);
;       LDA_(A3, 1, 1); MMA_(A2, B1, 0);
;       MMA_(A3, B1, 1);
;     ...
;     if constexpr (RING3) {
;       if (t + 2 < nt) asm volatile("s_waitcnt vmcnt(6)" ::: "memory");
;       else asm volatile("s_waitcnt vmcnt(0)" ::: "memory");
;       asm volatile("s_waitcnt lgkmcnt(0)" ::: "memory");
;       __builtin_amdgcn_s_barrier();
;       cur3 = (cur3 == 2) ? 0 : cur3 + 1;
;       nxt3 = (nxt3 == 2) ? 0 : nxt3 + 1;
;     } else {
;       asm volatile("s_waitcnt vmcnt(0)" ::: "memory");
;       __syncthreads();
;     }
.Lg_rot819_bplain:
	ds_read_b128 v[186:189], v178 offset:33792
	v_mfma_f32_16x16x32_bf16 v[60:63], v[138:141], v[170:173], v[60:63]
	v_mfma_f32_16x16x32_bf16 v[56:59], v[142:145], v[170:173], v[56:59]
	ds_read_b128 v[194:197], v178 offset:35840
	v_mfma_f32_16x16x32_bf16 v[52:55], v[146:149], v[170:173], v[52:55]
	v_mfma_f32_16x16x32_bf16 v[48:51], v[150:153], v[170:173], v[48:51]
	ds_read_b128 v[198:201], v178 offset:37888
	v_mfma_f32_16x16x32_bf16 v[44:47], v[138:141], v[154:157], v[44:47]
	v_mfma_f32_16x16x32_bf16 v[40:43], v[142:145], v[154:157], v[40:43]
	ds_read_b128 v[218:221], v178 offset:39936
	v_mfma_f32_16x16x32_bf16 v[36:39], v[146:149], v[154:157], v[36:39]
	v_mfma_f32_16x16x32_bf16 v[32:35], v[150:153], v[154:157], v[32:35]
	ds_read_b128 v[154:157], v137 offset:1024
	v_mfma_f32_16x16x32_bf16 v[28:31], v[138:141], v[158:161], v[28:31]
	v_mfma_f32_16x16x32_bf16 v[24:27], v[142:145], v[158:161], v[24:27]
	ds_read_b128 v[182:185], v137 offset:3072
	v_mfma_f32_16x16x32_bf16 v[20:23], v[146:149], v[158:161], v[20:23]
	v_mfma_f32_16x16x32_bf16 v[16:19], v[150:153], v[158:161], v[16:19]
	ds_read_b128 v[158:161], v137 offset:5120
	v_mfma_f32_16x16x32_bf16 v[8:11], v[138:141], v[162:165], v[8:11]
	v_mfma_f32_16x16x32_bf16 v[4:7], v[142:145], v[162:165], v[4:7]
	ds_read_b128 v[138:141], v137 offset:7168
	v_mfma_f32_16x16x32_bf16 v[0:3], v[146:149], v[162:165], v[0:3]
	v_mfma_f32_16x16x32_bf16 v[12:15], v[150:153], v[162:165], v[12:15]
	ds_read_b128 v[190:193], v137 offset:9216
	s_waitcnt lgkmcnt(4)
	v_mfma_f32_16x16x32_bf16 v[124:127], v[186:189], v[154:157], v[124:127]
	v_mfma_f32_16x16x32_bf16 v[120:123], v[194:197], v[154:157], v[120:123]
	v_mfma_f32_16x16x32_bf16 v[116:119], v[198:201], v[154:157], v[116:119]
	v_mfma_f32_16x16x32_bf16 v[112:115], v[218:221], v[154:157], v[112:115]
	ds_read_b128 v[222:225], v137 offset:11264
	s_waitcnt lgkmcnt(4)
	v_mfma_f32_16x16x32_bf16 v[108:111], v[186:189], v[182:185], v[108:111]
	v_mfma_f32_16x16x32_bf16 v[104:107], v[194:197], v[182:185], v[104:107]
	v_mfma_f32_16x16x32_bf16 v[100:103], v[198:201], v[182:185], v[100:103]
	v_mfma_f32_16x16x32_bf16 v[96:99], v[218:221], v[182:185], v[96:99]
	ds_read_b128 v[226:229], v137 offset:13312
	s_waitcnt lgkmcnt(4)
	v_mfma_f32_16x16x32_bf16 v[92:95], v[186:189], v[158:161], v[92:95]
	v_mfma_f32_16x16x32_bf16 v[88:91], v[194:197], v[158:161], v[88:91]
	v_mfma_f32_16x16x32_bf16 v[84:87], v[198:201], v[158:161], v[84:87]
	v_mfma_f32_16x16x32_bf16 v[80:83], v[218:221], v[158:161], v[80:83]
	ds_read_b128 v[230:233], v137 offset:15360
	s_waitcnt lgkmcnt(4)
	v_mfma_f32_16x16x32_bf16 v[76:79], v[186:189], v[138:141], v[76:79]
	v_mfma_f32_16x16x32_bf16 v[72:75], v[194:197], v[138:141], v[72:75]
	v_mfma_f32_16x16x32_bf16 v[68:71], v[198:201], v[138:141], v[68:71]
	v_mfma_f32_16x16x32_bf16 v[64:67], v[218:221], v[138:141], v[64:67]
	s_waitcnt lgkmcnt(0)
	s_cmp_lg_u32 s26, 0
	s_cbranch_scc1 .Lg_rot819_ectl
	s_waitcnt vmcnt(0)
.Lg_rot819_ectl:
	s_add_i32 s1, s1, 64
	s_add_i32 s17, s17, 0x10000
	s_add_i32 s18, s18, 1
	s_cmpk_lg_i32 s1, 0x100
	s_barrier
	s_cbranch_scc1 .LBB0_819
	v_mfma_f32_16x16x32_bf16 v[60:63], v[186:189], v[190:193], v[60:63]
	v_mfma_f32_16x16x32_bf16 v[56:59], v[194:197], v[190:193], v[56:59]
	v_mfma_f32_16x16x32_bf16 v[52:55], v[198:201], v[190:193], v[52:55]
	v_mfma_f32_16x16x32_bf16 v[48:51], v[218:221], v[190:193], v[48:51]
	v_mfma_f32_16x16x32_bf16 v[44:47], v[186:189], v[222:225], v[44:47]
	v_mfma_f32_16x16x32_bf16 v[40:43], v[194:197], v[222:225], v[40:43]
	v_mfma_f32_16x16x32_bf16 v[36:39], v[198:201], v[222:225], v[36:39]
	v_mfma_f32_16x16x32_bf16 v[32:35], v[218:221], v[222:225], v[32:35]
	v_mfma_f32_16x16x32_bf16 v[28:31], v[186:189], v[226:229], v[28:31]
	v_mfma_f32_16x16x32_bf16 v[24:27], v[194:197], v[226:229], v[24:27]
	v_mfma_f32_16x16x32_bf16 v[20:23], v[198:201], v[226:229], v[20:23]
	v_mfma_f32_16x16x32_bf16 v[16:19], v[218:221], v[226:229], v[16:19]
	v_mfma_f32_16x16x32_bf16 v[8:11], v[186:189], v[230:233], v[8:11]
	v_mfma_f32_16x16x32_bf16 v[4:7], v[194:197], v[230:233], v[4:7]
	v_mfma_f32_16x16x32_bf16 v[0:3], v[198:201], v[230:233], v[0:3]
	v_mfma_f32_16x16x32_bf16 v[12:15], v[218:221], v[230:233], v[12:15]
	s_nop 7
	s_nop 1
